# Proj (w_in) fast-path stores plain instead of sc1; on top of v28
# baseline (speedup 1.0000x reference)
; __device__ __forceinline__ u32x4 pack8(const f32x4 a, const f32x4 b) { u32x4 w; w.x = cvt_pk_bf16(a[0], a[1]); w.y = cvt_pk_bf16(a[2], a[3]); w.z = cvt_pk_bf16(b[0], b[1]); w.w = cvt_pk_bf16(b[2], b[3]); return w; }
;     __device__ __forceinline__ void operator()(const f32x4 (&acc)[2][2][4][2], const Unit& u, int wr, int wc, int fr, int fq) const {
;         const int row0 = u.pm * 256 + wr * 64 + fr; const int kind = u.pn < 7 ? 0 : (u.pn < 12 ? 1 : 2);
;         bf16_t* base = kind == 0 ? P1 : P2; const int ld = kind == 0 ? P1W : P2W; const int col0 = (kind == 0 ? u.pn : u.pn - 7) * 256 + wc * 32 + 8 * fq;
;         const float c3 = kind == 1 ? -LOG2E_ * 1.5957691216f * 0.044715f : 0.f, c1 = kind == 1 ? -LOG2E_ * 1.5957691216f : -LOG2E_;
; #pragma unroll
;         for (int ai = 0; ai < 2; ++ai)
; #pragma unroll
;             for (int m = 0; m < 4; ++m) {
;                 const int row = row0 + ai * 128 + m * 16; const float rs = (u.pm == pm0) ? RS[row & 255] : row_rstd(ss, row);
; #pragma unroll
;                 for (int bj = 0; bj < 2; ++bj) {
;                     f32x4 v[2], e[2];
; #pragma unroll
;                     for (int n = 0; n < 2; ++n) { v[n] = acc[ai][bj][m][n] * rs; e[n] = v[n] * ((v[n] * v[n]) * c3 + c1); }
;                     if (kind != 0) {
; #pragma unroll
;                         for (int n = 0; n < 2; ++n)
; #pragma unroll
;                             for (int j = 0; j < 4; ++j) e[n][j] = __builtin_amdgcn_exp2f(e[n][j]);
; #pragma unroll
;                         for (int n = 0; n < 2; ++n) e[n] = e[n] + 1.0f;
; #pragma unroll
;                         for (int n = 0; n < 2; ++n)
; #pragma unroll
;                             for (int j = 0; j < 4; ++j) e[n][j] = __builtin_amdgcn_rcpf(e[n][j]);
;                         if (kind == 1) { v[0] = v[0] * e[0]; v[1] = v[1] * e[1]; } else { v[0] = e[0]; v[1] = e[1]; }
;                     }
;                     __builtin_nontemporal_store(pack8(v[0], v[1]), (u32x4*)(base + (size_t)row * ld + col0 + bj * 128));
.LBB0_495:
	s_cmp_lg_u32 s4, s24
	s_cbranch_scc1 .Lpj_slow
	v_lshl_add_u32 v140, s4, 8, v160
	s_cmp_lt_i32 s6, 7
	s_cbranch_scc1 .Lpj_k0
	s_cmp_lt_i32 s6, 12
	s_cbranch_scc1 .Lpj_k1
	s_add_i32 s13, s6, -7
	s_lshl_b32 s13, s13, 8
	v_or_b32_e32 v141, s13, v163
	v_mul_u32_u24_e32 v140, 0x1a00, v140
	v_lshl_add_u32 v140, v141, 1, v140
	v_mov_b32_e32 v146, 0xbfb8aa3b
	v_mov_b32_e32 v147, 0xbfb8aa3b
	s_waitcnt lgkmcnt(7)
	v_mov_b32_e32 v138, v224
	v_pk_mul_f32 v[126:127], v[126:127], v[138:139] op_sel_hi:[1,0]
	v_pk_mul_f32 v[128:129], v[128:129], v[138:139] op_sel_hi:[1,0]
	v_pk_mul_f32 v[122:123], v[122:123], v[138:139] op_sel_hi:[1,0]
	v_pk_mul_f32 v[124:125], v[124:125], v[138:139] op_sel_hi:[1,0]
	v_pk_mul_f32 v[166:167], v[126:127], v[146:147]
	v_pk_mul_f32 v[168:169], v[128:129], v[146:147]
	v_pk_mul_f32 v[170:171], v[122:123], v[146:147]
	v_pk_mul_f32 v[172:173], v[124:125], v[146:147]
	v_exp_f32_e32 v166, v166
	v_exp_f32_e32 v167, v167
	v_exp_f32_e32 v168, v168
	v_exp_f32_e32 v169, v169
	v_exp_f32_e32 v170, v170
	v_exp_f32_e32 v171, v171
	v_exp_f32_e32 v172, v172
	v_exp_f32_e32 v173, v173
	v_pk_add_f32 v[166:167], v[166:167], 1.0 op_sel_hi:[1,0]
	v_pk_add_f32 v[168:169], v[168:169], 1.0 op_sel_hi:[1,0]
	v_pk_add_f32 v[170:171], v[170:171], 1.0 op_sel_hi:[1,0]
	v_pk_add_f32 v[172:173], v[172:173], 1.0 op_sel_hi:[1,0]
	v_rcp_f32_e32 v166, v166
	v_rcp_f32_e32 v167, v167
	v_rcp_f32_e32 v168, v168
	v_rcp_f32_e32 v169, v169
	v_rcp_f32_e32 v170, v170
	v_rcp_f32_e32 v171, v171
	v_rcp_f32_e32 v172, v172
	v_rcp_f32_e32 v173, v173
	v_cvt_pk_bf16_f32 v126, v166, v167
	v_cvt_pk_bf16_f32 v127, v168, v169
	v_cvt_pk_bf16_f32 v128, v170, v171
	v_cvt_pk_bf16_f32 v129, v172, v173
	global_store_dwordx4 v140, v[126:129], s[56:57]
	v_pk_mul_f32 v[118:119], v[118:119], v[138:139] op_sel_hi:[1,0]
	v_pk_mul_f32 v[120:121], v[120:121], v[138:139] op_sel_hi:[1,0]
	v_pk_mul_f32 v[114:115], v[114:115], v[138:139] op_sel_hi:[1,0]
	v_pk_mul_f32 v[116:117], v[116:117], v[138:139] op_sel_hi:[1,0]
	v_pk_mul_f32 v[166:167], v[118:119], v[146:147]
	v_pk_mul_f32 v[168:169], v[120:121], v[146:147]
	v_pk_mul_f32 v[170:171], v[114:115], v[146:147]
	v_pk_mul_f32 v[172:173], v[116:117], v[146:147]
	v_exp_f32_e32 v166, v166
	v_exp_f32_e32 v167, v167
	v_exp_f32_e32 v168, v168
	v_exp_f32_e32 v169, v169
	v_exp_f32_e32 v170, v170
	v_exp_f32_e32 v171, v171
	v_exp_f32_e32 v172, v172
	v_exp_f32_e32 v173, v173
	v_pk_add_f32 v[166:167], v[166:167], 1.0 op_sel_hi:[1,0]
	v_pk_add_f32 v[168:169], v[168:169], 1.0 op_sel_hi:[1,0]
	v_pk_add_f32 v[170:171], v[170:171], 1.0 op_sel_hi:[1,0]
	v_pk_add_f32 v[172:173], v[172:173], 1.0 op_sel_hi:[1,0]
	v_rcp_f32_e32 v166, v166
	v_rcp_f32_e32 v167, v167
	v_rcp_f32_e32 v168, v168
	v_rcp_f32_e32 v169, v169
	v_rcp_f32_e32 v170, v170
	v_rcp_f32_e32 v171, v171
	v_rcp_f32_e32 v172, v172
	v_rcp_f32_e32 v173, v173
	v_cvt_pk_bf16_f32 v118, v166, v167
	v_cvt_pk_bf16_f32 v119, v168, v169
	v_cvt_pk_bf16_f32 v120, v170, v171
	v_cvt_pk_bf16_f32 v121, v172, v173
	global_store_dwordx4 v140, v[118:121], s[56:57] offset:256
	s_waitcnt lgkmcnt(6)
	v_mov_b32_e32 v138, v225
	v_add_u32_e32 v141, 0x1a000, v140
	v_pk_mul_f32 v[110:111], v[110:111], v[138:139] op_sel_hi:[1,0]
	v_pk_mul_f32 v[112:113], v[112:113], v[138:139] op_sel_hi:[1,0]
	v_pk_mul_f32 v[106:107], v[106:107], v[138:139] op_sel_hi:[1,0]
	v_pk_mul_f32 v[108:109], v[108:109], v[138:139] op_sel_hi:[1,0]
	v_pk_mul_f32 v[166:167], v[110:111], v[146:147]
	v_pk_mul_f32 v[168:169], v[112:113], v[146:147]
	v_pk_mul_f32 v[170:171], v[106:107], v[146:147]
	v_pk_mul_f32 v[172:173], v[108:109], v[146:147]
	v_exp_f32_e32 v166, v166
	v_exp_f32_e32 v167, v167
	v_exp_f32_e32 v168, v168
	v_exp_f32_e32 v169, v169
	v_exp_f32_e32 v170, v170
	v_exp_f32_e32 v171, v171
	v_exp_f32_e32 v172, v172
	v_exp_f32_e32 v173, v173
	v_pk_add_f32 v[166:167], v[166:167], 1.0 op_sel_hi:[1,0]
	v_pk_add_f32 v[168:169], v[168:169], 1.0 op_sel_hi:[1,0]
	v_pk_add_f32 v[170:171], v[170:171], 1.0 op_sel_hi:[1,0]
	v_pk_add_f32 v[172:173], v[172:173], 1.0 op_sel_hi:[1,0]
	v_rcp_f32_e32 v166, v166
	v_rcp_f32_e32 v167, v167
	v_rcp_f32_e32 v168, v168
	v_rcp_f32_e32 v169, v169
	v_rcp_f32_e32 v170, v170
	v_rcp_f32_e32 v171, v171
	v_rcp_f32_e32 v172, v172
	v_rcp_f32_e32 v173, v173
	v_cvt_pk_bf16_f32 v110, v166, v167
	v_cvt_pk_bf16_f32 v111, v168, v169
	v_cvt_pk_bf16_f32 v112, v170, v171
	v_cvt_pk_bf16_f32 v113, v172, v173
	global_store_dwordx4 v141, v[110:113], s[56:57]
	v_pk_mul_f32 v[102:103], v[102:103], v[138:139] op_sel_hi:[1,0]
	v_pk_mul_f32 v[104:105], v[104:105], v[138:139] op_sel_hi:[1,0]
	v_pk_mul_f32 v[98:99], v[98:99], v[138:139] op_sel_hi:[1,0]
	v_pk_mul_f32 v[100:101], v[100:101], v[138:139] op_sel_hi:[1,0]
	v_pk_mul_f32 v[166:167], v[102:103], v[146:147]
	v_pk_mul_f32 v[168:169], v[104:105], v[146:147]
	v_pk_mul_f32 v[170:171], v[98:99], v[146:147]
	v_pk_mul_f32 v[172:173], v[100:101], v[146:147]
	v_exp_f32_e32 v166, v166
	v_exp_f32_e32 v167, v167
	v_exp_f32_e32 v168, v168
	v_exp_f32_e32 v169, v169
	v_exp_f32_e32 v170, v170
	v_exp_f32_e32 v171, v171
	v_exp_f32_e32 v172, v172
	v_exp_f32_e32 v173, v173
	v_pk_add_f32 v[166:167], v[166:167], 1.0 op_sel_hi:[1,0]
	v_pk_add_f32 v[168:169], v[168:169], 1.0 op_sel_hi:[1,0]
	v_pk_add_f32 v[170:171], v[170:171], 1.0 op_sel_hi:[1,0]
	v_pk_add_f32 v[172:173], v[172:173], 1.0 op_sel_hi:[1,0]
	v_rcp_f32_e32 v166, v166
	v_rcp_f32_e32 v167, v167
	v_rcp_f32_e32 v168, v168
	v_rcp_f32_e32 v169, v169
	v_rcp_f32_e32 v170, v170
	v_rcp_f32_e32 v171, v171
	v_rcp_f32_e32 v172, v172
	v_rcp_f32_e32 v173, v173
	v_cvt_pk_bf16_f32 v102, v166, v167
	v_cvt_pk_bf16_f32 v103, v168, v169
	v_cvt_pk_bf16_f32 v104, v170, v171
	v_cvt_pk_bf16_f32 v105, v172, v173
	global_store_dwordx4 v141, v[102:105], s[56:57] offset:256
	s_waitcnt lgkmcnt(5)
; __device__ __forceinline__ u32x4 pack8(const f32x4 a, const f32x4 b) { u32x4 w; w.x = cvt_pk_bf16(a[0], a[1]); w.y = cvt_pk_bf16(a[2], a[3]); w.z = cvt_pk_bf16(b[0], b[1]); w.w = cvt_pk_bf16(b[2], b[3]); return w; }
;     __device__ __forceinline__ void operator()(const f32x4 (&acc)[2][2][4][2], const Unit& u, int wr, int wc, int fr, int fq) const {
;     ...
;                 const int row = row0 + ai * 128 + m * 16; const float rs = (u.pm == pm0) ? RS[row & 255] : row_rstd(ss, row);
; #pragma unroll
;                 for (int bj = 0; bj < 2; ++bj) {
;                     f32x4 v[2], e[2];
; #pragma unroll
;                     for (int n = 0; n < 2; ++n) { v[n] = acc[ai][bj][m][n] * rs; e[n] = v[n] * ((v[n] * v[n]) * c3 + c1); }
;                     if (kind != 0) {
; #pragma unroll
;                         for (int n = 0; n < 2; ++n)
; #pragma unroll
;                             for (int j = 0; j < 4; ++j) e[n][j] = __builtin_amdgcn_exp2f(e[n][j]);
; #pragma unroll
;                         for (int n = 0; n < 2; ++n) e[n] = e[n] + 1.0f;
; #pragma unroll
;                         for (int n = 0; n < 2; ++n)
; #pragma unroll
;                             for (int j = 0; j < 4; ++j) e[n][j] = __builtin_amdgcn_rcpf(e[n][j]);
;                         if (kind == 1) { v[0] = v[0] * e[0]; v[1] = v[1] * e[1]; } else { v[0] = e[0]; v[1] = e[1]; }
;                     }
;                     __builtin_nontemporal_store(pack8(v[0], v[1]), (u32x4*)(base + (size_t)row * ld + col0 + bj * 128));
	v_mov_b32_e32 v138, v226
	v_add_u32_e32 v141, 0x34000, v140
	v_pk_mul_f32 v[94:95], v[94:95], v[138:139] op_sel_hi:[1,0]
	v_pk_mul_f32 v[96:97], v[96:97], v[138:139] op_sel_hi:[1,0]
	v_pk_mul_f32 v[90:91], v[90:91], v[138:139] op_sel_hi:[1,0]
	v_pk_mul_f32 v[92:93], v[92:93], v[138:139] op_sel_hi:[1,0]
	v_pk_mul_f32 v[166:167], v[94:95], v[146:147]
	v_pk_mul_f32 v[168:169], v[96:97], v[146:147]
	v_pk_mul_f32 v[170:171], v[90:91], v[146:147]
	v_pk_mul_f32 v[172:173], v[92:93], v[146:147]
	v_exp_f32_e32 v166, v166
	v_exp_f32_e32 v167, v167
	v_exp_f32_e32 v168, v168
	v_exp_f32_e32 v169, v169
	v_exp_f32_e32 v170, v170
	v_exp_f32_e32 v171, v171
	v_exp_f32_e32 v172, v172
	v_exp_f32_e32 v173, v173
	v_pk_add_f32 v[166:167], v[166:167], 1.0 op_sel_hi:[1,0]
	v_pk_add_f32 v[168:169], v[168:169], 1.0 op_sel_hi:[1,0]
	v_pk_add_f32 v[170:171], v[170:171], 1.0 op_sel_hi:[1,0]
	v_pk_add_f32 v[172:173], v[172:173], 1.0 op_sel_hi:[1,0]
	v_rcp_f32_e32 v166, v166
	v_rcp_f32_e32 v167, v167
	v_rcp_f32_e32 v168, v168
	v_rcp_f32_e32 v169, v169
	v_rcp_f32_e32 v170, v170
	v_rcp_f32_e32 v171, v171
	v_rcp_f32_e32 v172, v172
	v_rcp_f32_e32 v173, v173
	v_cvt_pk_bf16_f32 v94, v166, v167
	v_cvt_pk_bf16_f32 v95, v168, v169
	v_cvt_pk_bf16_f32 v96, v170, v171
	v_cvt_pk_bf16_f32 v97, v172, v173
	global_store_dwordx4 v141, v[94:97], s[56:57]
	v_pk_mul_f32 v[86:87], v[86:87], v[138:139] op_sel_hi:[1,0]
	v_pk_mul_f32 v[88:89], v[88:89], v[138:139] op_sel_hi:[1,0]
	v_pk_mul_f32 v[82:83], v[82:83], v[138:139] op_sel_hi:[1,0]
	v_pk_mul_f32 v[84:85], v[84:85], v[138:139] op_sel_hi:[1,0]
	v_pk_mul_f32 v[166:167], v[86:87], v[146:147]
	v_pk_mul_f32 v[168:169], v[88:89], v[146:147]
	v_pk_mul_f32 v[170:171], v[82:83], v[146:147]
	v_pk_mul_f32 v[172:173], v[84:85], v[146:147]
	v_exp_f32_e32 v166, v166
	v_exp_f32_e32 v167, v167
	v_exp_f32_e32 v168, v168
	v_exp_f32_e32 v169, v169
	v_exp_f32_e32 v170, v170
	v_exp_f32_e32 v171, v171
	v_exp_f32_e32 v172, v172
	v_exp_f32_e32 v173, v173
	v_pk_add_f32 v[166:167], v[166:167], 1.0 op_sel_hi:[1,0]
	v_pk_add_f32 v[168:169], v[168:169], 1.0 op_sel_hi:[1,0]
	v_pk_add_f32 v[170:171], v[170:171], 1.0 op_sel_hi:[1,0]
	v_pk_add_f32 v[172:173], v[172:173], 1.0 op_sel_hi:[1,0]
	v_rcp_f32_e32 v166, v166
	v_rcp_f32_e32 v167, v167
	v_rcp_f32_e32 v168, v168
	v_rcp_f32_e32 v169, v169
	v_rcp_f32_e32 v170, v170
	v_rcp_f32_e32 v171, v171
	v_rcp_f32_e32 v172, v172
	v_rcp_f32_e32 v173, v173
	v_cvt_pk_bf16_f32 v86, v166, v167
	v_cvt_pk_bf16_f32 v87, v168, v169
	v_cvt_pk_bf16_f32 v88, v170, v171
	v_cvt_pk_bf16_f32 v89, v172, v173
	global_store_dwordx4 v141, v[86:89], s[56:57] offset:256
	s_waitcnt lgkmcnt(4)
	v_mov_b32_e32 v138, v227
	v_add_u32_e32 v141, 0x4e000, v140
	v_pk_mul_f32 v[78:79], v[78:79], v[138:139] op_sel_hi:[1,0]
	v_pk_mul_f32 v[80:81], v[80:81], v[138:139] op_sel_hi:[1,0]
	v_pk_mul_f32 v[74:75], v[74:75], v[138:139] op_sel_hi:[1,0]
	v_pk_mul_f32 v[76:77], v[76:77], v[138:139] op_sel_hi:[1,0]
	v_pk_mul_f32 v[166:167], v[78:79], v[146:147]
	v_pk_mul_f32 v[168:169], v[80:81], v[146:147]
	v_pk_mul_f32 v[170:171], v[74:75], v[146:147]
	v_pk_mul_f32 v[172:173], v[76:77], v[146:147]
	v_exp_f32_e32 v166, v166
	v_exp_f32_e32 v167, v167
	v_exp_f32_e32 v168, v168
	v_exp_f32_e32 v169, v169
	v_exp_f32_e32 v170, v170
	v_exp_f32_e32 v171, v171
	v_exp_f32_e32 v172, v172
	v_exp_f32_e32 v173, v173
	v_pk_add_f32 v[166:167], v[166:167], 1.0 op_sel_hi:[1,0]
	v_pk_add_f32 v[168:169], v[168:169], 1.0 op_sel_hi:[1,0]
	v_pk_add_f32 v[170:171], v[170:171], 1.0 op_sel_hi:[1,0]
	v_pk_add_f32 v[172:173], v[172:173], 1.0 op_sel_hi:[1,0]
	v_rcp_f32_e32 v166, v166
	v_rcp_f32_e32 v167, v167
	v_rcp_f32_e32 v168, v168
	v_rcp_f32_e32 v169, v169
	v_rcp_f32_e32 v170, v170
	v_rcp_f32_e32 v171, v171
	v_rcp_f32_e32 v172, v172
	v_rcp_f32_e32 v173, v173
	v_cvt_pk_bf16_f32 v78, v166, v167
	v_cvt_pk_bf16_f32 v79, v168, v169
	v_cvt_pk_bf16_f32 v80, v170, v171
	v_cvt_pk_bf16_f32 v81, v172, v173
	global_store_dwordx4 v141, v[78:81], s[56:57]
	v_pk_mul_f32 v[70:71], v[70:71], v[138:139] op_sel_hi:[1,0]
	v_pk_mul_f32 v[72:73], v[72:73], v[138:139] op_sel_hi:[1,0]
	v_pk_mul_f32 v[66:67], v[66:67], v[138:139] op_sel_hi:[1,0]
	v_pk_mul_f32 v[68:69], v[68:69], v[138:139] op_sel_hi:[1,0]
	v_pk_mul_f32 v[166:167], v[70:71], v[146:147]
	v_pk_mul_f32 v[168:169], v[72:73], v[146:147]
	v_pk_mul_f32 v[170:171], v[66:67], v[146:147]
	v_pk_mul_f32 v[172:173], v[68:69], v[146:147]
	v_exp_f32_e32 v166, v166
	v_exp_f32_e32 v167, v167
	v_exp_f32_e32 v168, v168
	v_exp_f32_e32 v169, v169
	v_exp_f32_e32 v170, v170
	v_exp_f32_e32 v171, v171
	v_exp_f32_e32 v172, v172
	v_exp_f32_e32 v173, v173
	v_pk_add_f32 v[166:167], v[166:167], 1.0 op_sel_hi:[1,0]
	v_pk_add_f32 v[168:169], v[168:169], 1.0 op_sel_hi:[1,0]
	v_pk_add_f32 v[170:171], v[170:171], 1.0 op_sel_hi:[1,0]
	v_pk_add_f32 v[172:173], v[172:173], 1.0 op_sel_hi:[1,0]
	v_rcp_f32_e32 v166, v166
	v_rcp_f32_e32 v167, v167
	v_rcp_f32_e32 v168, v168
	v_rcp_f32_e32 v169, v169
	v_rcp_f32_e32 v170, v170
	v_rcp_f32_e32 v171, v171
	v_rcp_f32_e32 v172, v172
	v_rcp_f32_e32 v173, v173
	v_cvt_pk_bf16_f32 v70, v166, v167
	v_cvt_pk_bf16_f32 v71, v168, v169
	v_cvt_pk_bf16_f32 v72, v170, v171
	v_cvt_pk_bf16_f32 v73, v172, v173
	global_store_dwordx4 v141, v[70:73], s[56:57] offset:256
	s_waitcnt lgkmcnt(3)
; __device__ __forceinline__ u32x4 pack8(const f32x4 a, const f32x4 b) { u32x4 w; w.x = cvt_pk_bf16(a[0], a[1]); w.y = cvt_pk_bf16(a[2], a[3]); w.z = cvt_pk_bf16(b[0], b[1]); w.w = cvt_pk_bf16(b[2], b[3]); return w; }
;     __device__ __forceinline__ void operator()(const f32x4 (&acc)[2][2][4][2], const Unit& u, int wr, int wc, int fr, int fq) const {
;     ...
;                 const int row = row0 + ai * 128 + m * 16; const float rs = (u.pm == pm0) ? RS[row & 255] : row_rstd(ss, row);
; #pragma unroll
;                 for (int bj = 0; bj < 2; ++bj) {
;                     f32x4 v[2], e[2];
; #pragma unroll
;                     for (int n = 0; n < 2; ++n) { v[n] = acc[ai][bj][m][n] * rs; e[n] = v[n] * ((v[n] * v[n]) * c3 + c1); }
;                     if (kind != 0) {
; #pragma unroll
;                         for (int n = 0; n < 2; ++n)
; #pragma unroll
;                             for (int j = 0; j < 4; ++j) e[n][j] = __builtin_amdgcn_exp2f(e[n][j]);
; #pragma unroll
;                         for (int n = 0; n < 2; ++n) e[n] = e[n] + 1.0f;
; #pragma unroll
;                         for (int n = 0; n < 2; ++n)
; #pragma unroll
;                             for (int j = 0; j < 4; ++j) e[n][j] = __builtin_amdgcn_rcpf(e[n][j]);
;                         if (kind == 1) { v[0] = v[0] * e[0]; v[1] = v[1] * e[1]; } else { v[0] = e[0]; v[1] = e[1]; }
;                     }
;                     __builtin_nontemporal_store(pack8(v[0], v[1]), (u32x4*)(base + (size_t)row * ld + col0 + bj * 128));
	v_mov_b32_e32 v138, v228
	v_add_u32_e32 v141, 0xd0000, v140
	v_pk_mul_f32 v[62:63], v[62:63], v[138:139] op_sel_hi:[1,0]
	v_pk_mul_f32 v[64:65], v[64:65], v[138:139] op_sel_hi:[1,0]
	v_pk_mul_f32 v[58:59], v[58:59], v[138:139] op_sel_hi:[1,0]
	v_pk_mul_f32 v[60:61], v[60:61], v[138:139] op_sel_hi:[1,0]
	v_pk_mul_f32 v[166:167], v[62:63], v[146:147]
	v_pk_mul_f32 v[168:169], v[64:65], v[146:147]
	v_pk_mul_f32 v[170:171], v[58:59], v[146:147]
	v_pk_mul_f32 v[172:173], v[60:61], v[146:147]
	v_exp_f32_e32 v166, v166
	v_exp_f32_e32 v167, v167
	v_exp_f32_e32 v168, v168
	v_exp_f32_e32 v169, v169
	v_exp_f32_e32 v170, v170
	v_exp_f32_e32 v171, v171
	v_exp_f32_e32 v172, v172
	v_exp_f32_e32 v173, v173
	v_pk_add_f32 v[166:167], v[166:167], 1.0 op_sel_hi:[1,0]
	v_pk_add_f32 v[168:169], v[168:169], 1.0 op_sel_hi:[1,0]
	v_pk_add_f32 v[170:171], v[170:171], 1.0 op_sel_hi:[1,0]
	v_pk_add_f32 v[172:173], v[172:173], 1.0 op_sel_hi:[1,0]
	v_rcp_f32_e32 v166, v166
	v_rcp_f32_e32 v167, v167
	v_rcp_f32_e32 v168, v168
	v_rcp_f32_e32 v169, v169
	v_rcp_f32_e32 v170, v170
	v_rcp_f32_e32 v171, v171
	v_rcp_f32_e32 v172, v172
	v_rcp_f32_e32 v173, v173
	v_cvt_pk_bf16_f32 v62, v166, v167
	v_cvt_pk_bf16_f32 v63, v168, v169
	v_cvt_pk_bf16_f32 v64, v170, v171
	v_cvt_pk_bf16_f32 v65, v172, v173
	global_store_dwordx4 v141, v[62:65], s[56:57]
	v_pk_mul_f32 v[54:55], v[54:55], v[138:139] op_sel_hi:[1,0]
	v_pk_mul_f32 v[56:57], v[56:57], v[138:139] op_sel_hi:[1,0]
	v_pk_mul_f32 v[50:51], v[50:51], v[138:139] op_sel_hi:[1,0]
	v_pk_mul_f32 v[52:53], v[52:53], v[138:139] op_sel_hi:[1,0]
	v_pk_mul_f32 v[166:167], v[54:55], v[146:147]
	v_pk_mul_f32 v[168:169], v[56:57], v[146:147]
	v_pk_mul_f32 v[170:171], v[50:51], v[146:147]
	v_pk_mul_f32 v[172:173], v[52:53], v[146:147]
	v_exp_f32_e32 v166, v166
	v_exp_f32_e32 v167, v167
	v_exp_f32_e32 v168, v168
	v_exp_f32_e32 v169, v169
	v_exp_f32_e32 v170, v170
	v_exp_f32_e32 v171, v171
	v_exp_f32_e32 v172, v172
	v_exp_f32_e32 v173, v173
	v_pk_add_f32 v[166:167], v[166:167], 1.0 op_sel_hi:[1,0]
	v_pk_add_f32 v[168:169], v[168:169], 1.0 op_sel_hi:[1,0]
	v_pk_add_f32 v[170:171], v[170:171], 1.0 op_sel_hi:[1,0]
	v_pk_add_f32 v[172:173], v[172:173], 1.0 op_sel_hi:[1,0]
	v_rcp_f32_e32 v166, v166
	v_rcp_f32_e32 v167, v167
	v_rcp_f32_e32 v168, v168
	v_rcp_f32_e32 v169, v169
	v_rcp_f32_e32 v170, v170
	v_rcp_f32_e32 v171, v171
	v_rcp_f32_e32 v172, v172
	v_rcp_f32_e32 v173, v173
	v_cvt_pk_bf16_f32 v54, v166, v167
	v_cvt_pk_bf16_f32 v55, v168, v169
	v_cvt_pk_bf16_f32 v56, v170, v171
	v_cvt_pk_bf16_f32 v57, v172, v173
	global_store_dwordx4 v141, v[54:57], s[56:57] offset:256
	s_waitcnt lgkmcnt(2)
	v_mov_b32_e32 v138, v229
	v_add_u32_e32 v141, 0xea000, v140
	v_pk_mul_f32 v[46:47], v[46:47], v[138:139] op_sel_hi:[1,0]
	v_pk_mul_f32 v[48:49], v[48:49], v[138:139] op_sel_hi:[1,0]
	v_pk_mul_f32 v[42:43], v[42:43], v[138:139] op_sel_hi:[1,0]
	v_pk_mul_f32 v[44:45], v[44:45], v[138:139] op_sel_hi:[1,0]
	v_pk_mul_f32 v[166:167], v[46:47], v[146:147]
	v_pk_mul_f32 v[168:169], v[48:49], v[146:147]
	v_pk_mul_f32 v[170:171], v[42:43], v[146:147]
	v_pk_mul_f32 v[172:173], v[44:45], v[146:147]
	v_exp_f32_e32 v166, v166
	v_exp_f32_e32 v167, v167
	v_exp_f32_e32 v168, v168
	v_exp_f32_e32 v169, v169
	v_exp_f32_e32 v170, v170
	v_exp_f32_e32 v171, v171
	v_exp_f32_e32 v172, v172
	v_exp_f32_e32 v173, v173
	v_pk_add_f32 v[166:167], v[166:167], 1.0 op_sel_hi:[1,0]
	v_pk_add_f32 v[168:169], v[168:169], 1.0 op_sel_hi:[1,0]
	v_pk_add_f32 v[170:171], v[170:171], 1.0 op_sel_hi:[1,0]
	v_pk_add_f32 v[172:173], v[172:173], 1.0 op_sel_hi:[1,0]
	v_rcp_f32_e32 v166, v166
	v_rcp_f32_e32 v167, v167
	v_rcp_f32_e32 v168, v168
	v_rcp_f32_e32 v169, v169
	v_rcp_f32_e32 v170, v170
	v_rcp_f32_e32 v171, v171
	v_rcp_f32_e32 v172, v172
	v_rcp_f32_e32 v173, v173
	v_cvt_pk_bf16_f32 v46, v166, v167
	v_cvt_pk_bf16_f32 v47, v168, v169
	v_cvt_pk_bf16_f32 v48, v170, v171
	v_cvt_pk_bf16_f32 v49, v172, v173
	global_store_dwordx4 v141, v[46:49], s[56:57]
	v_pk_mul_f32 v[38:39], v[38:39], v[138:139] op_sel_hi:[1,0]
	v_pk_mul_f32 v[40:41], v[40:41], v[138:139] op_sel_hi:[1,0]
	v_pk_mul_f32 v[34:35], v[34:35], v[138:139] op_sel_hi:[1,0]
	v_pk_mul_f32 v[36:37], v[36:37], v[138:139] op_sel_hi:[1,0]
	v_pk_mul_f32 v[166:167], v[38:39], v[146:147]
	v_pk_mul_f32 v[168:169], v[40:41], v[146:147]
	v_pk_mul_f32 v[170:171], v[34:35], v[146:147]
	v_pk_mul_f32 v[172:173], v[36:37], v[146:147]
	v_exp_f32_e32 v166, v166
	v_exp_f32_e32 v167, v167
	v_exp_f32_e32 v168, v168
	v_exp_f32_e32 v169, v169
	v_exp_f32_e32 v170, v170
	v_exp_f32_e32 v171, v171
	v_exp_f32_e32 v172, v172
	v_exp_f32_e32 v173, v173
	v_pk_add_f32 v[166:167], v[166:167], 1.0 op_sel_hi:[1,0]
	v_pk_add_f32 v[168:169], v[168:169], 1.0 op_sel_hi:[1,0]
	v_pk_add_f32 v[170:171], v[170:171], 1.0 op_sel_hi:[1,0]
	v_pk_add_f32 v[172:173], v[172:173], 1.0 op_sel_hi:[1,0]
	v_rcp_f32_e32 v166, v166
	v_rcp_f32_e32 v167, v167
	v_rcp_f32_e32 v168, v168
	v_rcp_f32_e32 v169, v169
	v_rcp_f32_e32 v170, v170
	v_rcp_f32_e32 v171, v171
	v_rcp_f32_e32 v172, v172
	v_rcp_f32_e32 v173, v173
	v_cvt_pk_bf16_f32 v38, v166, v167
	v_cvt_pk_bf16_f32 v39, v168, v169
	v_cvt_pk_bf16_f32 v40, v170, v171
	v_cvt_pk_bf16_f32 v41, v172, v173
	global_store_dwordx4 v141, v[38:41], s[56:57] offset:256
	s_waitcnt lgkmcnt(1)
; __device__ __forceinline__ u32x4 pack8(const f32x4 a, const f32x4 b) { u32x4 w; w.x = cvt_pk_bf16(a[0], a[1]); w.y = cvt_pk_bf16(a[2], a[3]); w.z = cvt_pk_bf16(b[0], b[1]); w.w = cvt_pk_bf16(b[2], b[3]); return w; }
;     __device__ __forceinline__ void operator()(const f32x4 (&acc)[2][2][4][2], const Unit& u, int wr, int wc, int fr, int fq) const {
;     ...
;                 const int row = row0 + ai * 128 + m * 16; const float rs = (u.pm == pm0) ? RS[row & 255] : row_rstd(ss, row);
; #pragma unroll
;                 for (int bj = 0; bj < 2; ++bj) {
;                     f32x4 v[2], e[2];
; #pragma unroll
;                     for (int n = 0; n < 2; ++n) { v[n] = acc[ai][bj][m][n] * rs; e[n] = v[n] * ((v[n] * v[n]) * c3 + c1); }
;                     if (kind != 0) {
; #pragma unroll
;                         for (int n = 0; n < 2; ++n)
; #pragma unroll
;                             for (int j = 0; j < 4; ++j) e[n][j] = __builtin_amdgcn_exp2f(e[n][j]);
; #pragma unroll
;                         for (int n = 0; n < 2; ++n) e[n] = e[n] + 1.0f;
; #pragma unroll
;                         for (int n = 0; n < 2; ++n)
; #pragma unroll
;                             for (int j = 0; j < 4; ++j) e[n][j] = __builtin_amdgcn_rcpf(e[n][j]);
;                         if (kind == 1) { v[0] = v[0] * e[0]; v[1] = v[1] * e[1]; } else { v[0] = e[0]; v[1] = e[1]; }
;                     }
;                     __builtin_nontemporal_store(pack8(v[0], v[1]), (u32x4*)(base + (size_t)row * ld + col0 + bj * 128));
;                 }
	v_mov_b32_e32 v138, v230
	v_add_u32_e32 v141, 0x104000, v140
	v_pk_mul_f32 v[30:31], v[30:31], v[138:139] op_sel_hi:[1,0]
	v_pk_mul_f32 v[32:33], v[32:33], v[138:139] op_sel_hi:[1,0]
	v_pk_mul_f32 v[26:27], v[26:27], v[138:139] op_sel_hi:[1,0]
	v_pk_mul_f32 v[28:29], v[28:29], v[138:139] op_sel_hi:[1,0]
	v_pk_mul_f32 v[166:167], v[30:31], v[146:147]
	v_pk_mul_f32 v[168:169], v[32:33], v[146:147]
	v_pk_mul_f32 v[170:171], v[26:27], v[146:147]
	v_pk_mul_f32 v[172:173], v[28:29], v[146:147]
	v_exp_f32_e32 v166, v166
	v_exp_f32_e32 v167, v167
	v_exp_f32_e32 v168, v168
	v_exp_f32_e32 v169, v169
	v_exp_f32_e32 v170, v170
	v_exp_f32_e32 v171, v171
	v_exp_f32_e32 v172, v172
	v_exp_f32_e32 v173, v173
	v_pk_add_f32 v[166:167], v[166:167], 1.0 op_sel_hi:[1,0]
	v_pk_add_f32 v[168:169], v[168:169], 1.0 op_sel_hi:[1,0]
	v_pk_add_f32 v[170:171], v[170:171], 1.0 op_sel_hi:[1,0]
	v_pk_add_f32 v[172:173], v[172:173], 1.0 op_sel_hi:[1,0]
	v_rcp_f32_e32 v166, v166
	v_rcp_f32_e32 v167, v167
	v_rcp_f32_e32 v168, v168
	v_rcp_f32_e32 v169, v169
	v_rcp_f32_e32 v170, v170
	v_rcp_f32_e32 v171, v171
	v_rcp_f32_e32 v172, v172
	v_rcp_f32_e32 v173, v173
	v_cvt_pk_bf16_f32 v30, v166, v167
	v_cvt_pk_bf16_f32 v31, v168, v169
	v_cvt_pk_bf16_f32 v32, v170, v171
	v_cvt_pk_bf16_f32 v33, v172, v173
	global_store_dwordx4 v141, v[30:33], s[56:57]
	v_pk_mul_f32 v[22:23], v[22:23], v[138:139] op_sel_hi:[1,0]
	v_pk_mul_f32 v[24:25], v[24:25], v[138:139] op_sel_hi:[1,0]
	v_pk_mul_f32 v[18:19], v[18:19], v[138:139] op_sel_hi:[1,0]
	v_pk_mul_f32 v[20:21], v[20:21], v[138:139] op_sel_hi:[1,0]
	v_pk_mul_f32 v[166:167], v[22:23], v[146:147]
	v_pk_mul_f32 v[168:169], v[24:25], v[146:147]
	v_pk_mul_f32 v[170:171], v[18:19], v[146:147]
	v_pk_mul_f32 v[172:173], v[20:21], v[146:147]
	v_exp_f32_e32 v166, v166
	v_exp_f32_e32 v167, v167
	v_exp_f32_e32 v168, v168
	v_exp_f32_e32 v169, v169
	v_exp_f32_e32 v170, v170
	v_exp_f32_e32 v171, v171
	v_exp_f32_e32 v172, v172
	v_exp_f32_e32 v173, v173
	v_pk_add_f32 v[166:167], v[166:167], 1.0 op_sel_hi:[1,0]
	v_pk_add_f32 v[168:169], v[168:169], 1.0 op_sel_hi:[1,0]
	v_pk_add_f32 v[170:171], v[170:171], 1.0 op_sel_hi:[1,0]
	v_pk_add_f32 v[172:173], v[172:173], 1.0 op_sel_hi:[1,0]
	v_rcp_f32_e32 v166, v166
	v_rcp_f32_e32 v167, v167
	v_rcp_f32_e32 v168, v168
	v_rcp_f32_e32 v169, v169
	v_rcp_f32_e32 v170, v170
	v_rcp_f32_e32 v171, v171
	v_rcp_f32_e32 v172, v172
	v_rcp_f32_e32 v173, v173
	v_cvt_pk_bf16_f32 v22, v166, v167
	v_cvt_pk_bf16_f32 v23, v168, v169
	v_cvt_pk_bf16_f32 v24, v170, v171
	v_cvt_pk_bf16_f32 v25, v172, v173
	global_store_dwordx4 v141, v[22:25], s[56:57] offset:256
	s_waitcnt lgkmcnt(0)
	v_mov_b32_e32 v138, v231
	v_add_u32_e32 v141, 0x11e000, v140
	v_pk_mul_f32 v[14:15], v[14:15], v[138:139] op_sel_hi:[1,0]
	v_pk_mul_f32 v[16:17], v[16:17], v[138:139] op_sel_hi:[1,0]
	v_pk_mul_f32 v[10:11], v[10:11], v[138:139] op_sel_hi:[1,0]
	v_pk_mul_f32 v[12:13], v[12:13], v[138:139] op_sel_hi:[1,0]
	v_pk_mul_f32 v[166:167], v[14:15], v[146:147]
	v_pk_mul_f32 v[168:169], v[16:17], v[146:147]
	v_pk_mul_f32 v[170:171], v[10:11], v[146:147]
	v_pk_mul_f32 v[172:173], v[12:13], v[146:147]
	v_exp_f32_e32 v166, v166
	v_exp_f32_e32 v167, v167
	v_exp_f32_e32 v168, v168
	v_exp_f32_e32 v169, v169
	v_exp_f32_e32 v170, v170
	v_exp_f32_e32 v171, v171
	v_exp_f32_e32 v172, v172
	v_exp_f32_e32 v173, v173
	v_pk_add_f32 v[166:167], v[166:167], 1.0 op_sel_hi:[1,0]
	v_pk_add_f32 v[168:169], v[168:169], 1.0 op_sel_hi:[1,0]
	v_pk_add_f32 v[170:171], v[170:171], 1.0 op_sel_hi:[1,0]
	v_pk_add_f32 v[172:173], v[172:173], 1.0 op_sel_hi:[1,0]
	v_rcp_f32_e32 v166, v166
	v_rcp_f32_e32 v167, v167
	v_rcp_f32_e32 v168, v168
	v_rcp_f32_e32 v169, v169
	v_rcp_f32_e32 v170, v170
	v_rcp_f32_e32 v171, v171
	v_rcp_f32_e32 v172, v172
	v_rcp_f32_e32 v173, v173
	v_cvt_pk_bf16_f32 v14, v166, v167
	v_cvt_pk_bf16_f32 v15, v168, v169
	v_cvt_pk_bf16_f32 v16, v170, v171
	v_cvt_pk_bf16_f32 v17, v172, v173
	global_store_dwordx4 v141, v[14:17], s[56:57]
	v_pk_mul_f32 v[6:7], v[6:7], v[138:139] op_sel_hi:[1,0]
	v_pk_mul_f32 v[8:9], v[8:9], v[138:139] op_sel_hi:[1,0]
	v_pk_mul_f32 v[2:3], v[2:3], v[138:139] op_sel_hi:[1,0]
	v_pk_mul_f32 v[4:5], v[4:5], v[138:139] op_sel_hi:[1,0]
	v_pk_mul_f32 v[166:167], v[6:7], v[146:147]
	v_pk_mul_f32 v[168:169], v[8:9], v[146:147]
	v_pk_mul_f32 v[170:171], v[2:3], v[146:147]
	v_pk_mul_f32 v[172:173], v[4:5], v[146:147]
	v_exp_f32_e32 v166, v166
	v_exp_f32_e32 v167, v167
	v_exp_f32_e32 v168, v168
	v_exp_f32_e32 v169, v169
	v_exp_f32_e32 v170, v170
	v_exp_f32_e32 v171, v171
	v_exp_f32_e32 v172, v172
	v_exp_f32_e32 v173, v173
	v_pk_add_f32 v[166:167], v[166:167], 1.0 op_sel_hi:[1,0]
	v_pk_add_f32 v[168:169], v[168:169], 1.0 op_sel_hi:[1,0]
	v_pk_add_f32 v[170:171], v[170:171], 1.0 op_sel_hi:[1,0]
	v_pk_add_f32 v[172:173], v[172:173], 1.0 op_sel_hi:[1,0]
	v_rcp_f32_e32 v166, v166
	v_rcp_f32_e32 v167, v167
	v_rcp_f32_e32 v168, v168
	v_rcp_f32_e32 v169, v169
	v_rcp_f32_e32 v170, v170
	v_rcp_f32_e32 v171, v171
	v_rcp_f32_e32 v172, v172
	v_rcp_f32_e32 v173, v173
	v_cvt_pk_bf16_f32 v6, v166, v167
	v_cvt_pk_bf16_f32 v7, v168, v169
	v_cvt_pk_bf16_f32 v8, v170, v171
	v_cvt_pk_bf16_f32 v9, v172, v173
	global_store_dwordx4 v141, v[6:9], s[56:57] offset:256
	s_branch .Lpj_done
; __device__ __forceinline__ u32x4 pack8(const f32x4 a, const f32x4 b) { u32x4 w; w.x = cvt_pk_bf16(a[0], a[1]); w.y = cvt_pk_bf16(a[2], a[3]); w.z = cvt_pk_bf16(b[0], b[1]); w.w = cvt_pk_bf16(b[2], b[3]); return w; }
;     __device__ __forceinline__ void operator()(const f32x4 (&acc)[2][2][4][2], const Unit& u, int wr, int wc, int fr, int fq) const {
;         const int row0 = u.pm * 256 + wr * 64 + fr; const int kind = u.pn < 7 ? 0 : (u.pn < 12 ? 1 : 2);
;         bf16_t* base = kind == 0 ? P1 : P2; const int ld = kind == 0 ? P1W : P2W; const int col0 = (kind == 0 ? u.pn : u.pn - 7) * 256 + wc * 32 + 8 * fq;
;         const float c3 = kind == 1 ? -LOG2E_ * 1.5957691216f * 0.044715f : 0.f, c1 = kind == 1 ? -LOG2E_ * 1.5957691216f : -LOG2E_;
; #pragma unroll
;         for (int ai = 0; ai < 2; ++ai)
; #pragma unroll
;             for (int m = 0; m < 4; ++m) {
;                 const int row = row0 + ai * 128 + m * 16; const float rs = (u.pm == pm0) ? RS[row & 255] : row_rstd(ss, row);
; #pragma unroll
;                 for (int bj = 0; bj < 2; ++bj) {
;                     f32x4 v[2], e[2];
; #pragma unroll
;                     for (int n = 0; n < 2; ++n) { v[n] = acc[ai][bj][m][n] * rs; e[n] = v[n] * ((v[n] * v[n]) * c3 + c1); }
;                     if (kind != 0) {
; #pragma unroll
;                         for (int n = 0; n < 2; ++n)
; #pragma unroll
;                             for (int j = 0; j < 4; ++j) e[n][j] = __builtin_amdgcn_exp2f(e[n][j]);
; #pragma unroll
;                         for (int n = 0; n < 2; ++n) e[n] = e[n] + 1.0f;
; #pragma unroll
;                         for (int n = 0; n < 2; ++n)
; #pragma unroll
;                             for (int j = 0; j < 4; ++j) e[n][j] = __builtin_amdgcn_rcpf(e[n][j]);
;                         if (kind == 1) { v[0] = v[0] * e[0]; v[1] = v[1] * e[1]; } else { v[0] = e[0]; v[1] = e[1]; }
;                     }
;                     __builtin_nontemporal_store(pack8(v[0], v[1]), (u32x4*)(base + (size_t)row * ld + col0 + bj * 128));
;                 }
.Lpj_k1:
	s_add_i32 s13, s6, -7
	s_lshl_b32 s13, s13, 8
	v_or_b32_e32 v141, s13, v163
	v_mul_u32_u24_e32 v140, 0x1a00, v140
	v_lshl_add_u32 v140, v141, 1, v140
	v_mov_b32_e32 v144, 0xbdd2d3e7
	v_mov_b32_e32 v145, 0xbdd2d3e7
	v_mov_b32_e32 v146, 0xc0135761
	v_mov_b32_e32 v147, 0xc0135761
	s_waitcnt lgkmcnt(7)
	v_mov_b32_e32 v138, v224
	v_pk_mul_f32 v[126:127], v[126:127], v[138:139] op_sel_hi:[1,0]
	v_pk_mul_f32 v[128:129], v[128:129], v[138:139] op_sel_hi:[1,0]
	v_pk_mul_f32 v[122:123], v[122:123], v[138:139] op_sel_hi:[1,0]
	v_pk_mul_f32 v[124:125], v[124:125], v[138:139] op_sel_hi:[1,0]
	v_pk_mul_f32 v[166:167], v[126:127], v[126:127]
	v_pk_mul_f32 v[168:169], v[128:129], v[128:129]
	v_pk_mul_f32 v[170:171], v[122:123], v[122:123]
	v_pk_mul_f32 v[172:173], v[124:125], v[124:125]
	v_pk_fma_f32 v[166:167], v[144:145], v[166:167], v[146:147]
	v_pk_fma_f32 v[168:169], v[144:145], v[168:169], v[146:147]
	v_pk_fma_f32 v[170:171], v[144:145], v[170:171], v[146:147]
	v_pk_fma_f32 v[172:173], v[144:145], v[172:173], v[146:147]
	v_pk_mul_f32 v[166:167], v[126:127], v[166:167]
	v_pk_mul_f32 v[168:169], v[128:129], v[168:169]
	v_pk_mul_f32 v[170:171], v[122:123], v[170:171]
	v_pk_mul_f32 v[172:173], v[124:125], v[172:173]
	v_exp_f32_e32 v166, v166
	v_exp_f32_e32 v167, v167
	v_exp_f32_e32 v168, v168
	v_exp_f32_e32 v169, v169
	v_exp_f32_e32 v170, v170
	v_exp_f32_e32 v171, v171
	v_exp_f32_e32 v172, v172
	v_exp_f32_e32 v173, v173
	v_pk_add_f32 v[166:167], v[166:167], 1.0 op_sel_hi:[1,0]
	v_pk_add_f32 v[168:169], v[168:169], 1.0 op_sel_hi:[1,0]
	v_pk_add_f32 v[170:171], v[170:171], 1.0 op_sel_hi:[1,0]
	v_pk_add_f32 v[172:173], v[172:173], 1.0 op_sel_hi:[1,0]
	v_rcp_f32_e32 v166, v166
	v_rcp_f32_e32 v167, v167
	v_rcp_f32_e32 v168, v168
	v_rcp_f32_e32 v169, v169
	v_rcp_f32_e32 v170, v170
	v_rcp_f32_e32 v171, v171
	v_rcp_f32_e32 v172, v172
	v_rcp_f32_e32 v173, v173
	v_pk_mul_f32 v[126:127], v[126:127], v[166:167]
	v_pk_mul_f32 v[128:129], v[128:129], v[168:169]
	v_pk_mul_f32 v[122:123], v[122:123], v[170:171]
	v_pk_mul_f32 v[124:125], v[124:125], v[172:173]
	v_cvt_pk_bf16_f32 v126, v126, v127
	v_cvt_pk_bf16_f32 v127, v128, v129
	v_cvt_pk_bf16_f32 v128, v122, v123
	v_cvt_pk_bf16_f32 v129, v124, v125
	global_store_dwordx4 v140, v[126:129], s[56:57]
	v_pk_mul_f32 v[118:119], v[118:119], v[138:139] op_sel_hi:[1,0]
	v_pk_mul_f32 v[120:121], v[120:121], v[138:139] op_sel_hi:[1,0]
	v_pk_mul_f32 v[114:115], v[114:115], v[138:139] op_sel_hi:[1,0]
	v_pk_mul_f32 v[116:117], v[116:117], v[138:139] op_sel_hi:[1,0]
	v_pk_mul_f32 v[166:167], v[118:119], v[118:119]
	v_pk_mul_f32 v[168:169], v[120:121], v[120:121]
	v_pk_mul_f32 v[170:171], v[114:115], v[114:115]
	v_pk_mul_f32 v[172:173], v[116:117], v[116:117]
	v_pk_fma_f32 v[166:167], v[144:145], v[166:167], v[146:147]
	v_pk_fma_f32 v[168:169], v[144:145], v[168:169], v[146:147]
	v_pk_fma_f32 v[170:171], v[144:145], v[170:171], v[146:147]
	v_pk_fma_f32 v[172:173], v[144:145], v[172:173], v[146:147]
	v_pk_mul_f32 v[166:167], v[118:119], v[166:167]
	v_pk_mul_f32 v[168:169], v[120:121], v[168:169]
	v_pk_mul_f32 v[170:171], v[114:115], v[170:171]
	v_pk_mul_f32 v[172:173], v[116:117], v[172:173]
	v_exp_f32_e32 v166, v166
	v_exp_f32_e32 v167, v167
	v_exp_f32_e32 v168, v168
	v_exp_f32_e32 v169, v169
	v_exp_f32_e32 v170, v170
	v_exp_f32_e32 v171, v171
	v_exp_f32_e32 v172, v172
	v_exp_f32_e32 v173, v173
	v_pk_add_f32 v[166:167], v[166:167], 1.0 op_sel_hi:[1,0]
	v_pk_add_f32 v[168:169], v[168:169], 1.0 op_sel_hi:[1,0]
	v_pk_add_f32 v[170:171], v[170:171], 1.0 op_sel_hi:[1,0]
	v_pk_add_f32 v[172:173], v[172:173], 1.0 op_sel_hi:[1,0]
	v_rcp_f32_e32 v166, v166
	v_rcp_f32_e32 v167, v167
	v_rcp_f32_e32 v168, v168
	v_rcp_f32_e32 v169, v169
	v_rcp_f32_e32 v170, v170
	v_rcp_f32_e32 v171, v171
	v_rcp_f32_e32 v172, v172
	v_rcp_f32_e32 v173, v173
	v_pk_mul_f32 v[118:119], v[118:119], v[166:167]
	v_pk_mul_f32 v[120:121], v[120:121], v[168:169]
	v_pk_mul_f32 v[114:115], v[114:115], v[170:171]
	v_pk_mul_f32 v[116:117], v[116:117], v[172:173]
	v_cvt_pk_bf16_f32 v118, v118, v119
	v_cvt_pk_bf16_f32 v119, v120, v121
	v_cvt_pk_bf16_f32 v120, v114, v115
	v_cvt_pk_bf16_f32 v121, v116, v117
	global_store_dwordx4 v140, v[118:121], s[56:57] offset:256
	s_waitcnt lgkmcnt(6)
; __device__ __forceinline__ u32x4 pack8(const f32x4 a, const f32x4 b) { u32x4 w; w.x = cvt_pk_bf16(a[0], a[1]); w.y = cvt_pk_bf16(a[2], a[3]); w.z = cvt_pk_bf16(b[0], b[1]); w.w = cvt_pk_bf16(b[2], b[3]); return w; }
;     __device__ __forceinline__ void operator()(const f32x4 (&acc)[2][2][4][2], const Unit& u, int wr, int wc, int fr, int fq) const {
;     ...
;                 const int row = row0 + ai * 128 + m * 16; const float rs = (u.pm == pm0) ? RS[row & 255] : row_rstd(ss, row);
; #pragma unroll
;                 for (int bj = 0; bj < 2; ++bj) {
;                     f32x4 v[2], e[2];
; #pragma unroll
;                     for (int n = 0; n < 2; ++n) { v[n] = acc[ai][bj][m][n] * rs; e[n] = v[n] * ((v[n] * v[n]) * c3 + c1); }
;                     if (kind != 0) {
; #pragma unroll
;                         for (int n = 0; n < 2; ++n)
; #pragma unroll
;                             for (int j = 0; j < 4; ++j) e[n][j] = __builtin_amdgcn_exp2f(e[n][j]);
; #pragma unroll
;                         for (int n = 0; n < 2; ++n) e[n] = e[n] + 1.0f;
; #pragma unroll
;                         for (int n = 0; n < 2; ++n)
; #pragma unroll
;                             for (int j = 0; j < 4; ++j) e[n][j] = __builtin_amdgcn_rcpf(e[n][j]);
;                         if (kind == 1) { v[0] = v[0] * e[0]; v[1] = v[1] * e[1]; } else { v[0] = e[0]; v[1] = e[1]; }
;                     }
;                     __builtin_nontemporal_store(pack8(v[0], v[1]), (u32x4*)(base + (size_t)row * ld + col0 + bj * 128));
;                 }
	v_mov_b32_e32 v138, v225
	v_add_u32_e32 v141, 0x1a000, v140
	v_pk_mul_f32 v[110:111], v[110:111], v[138:139] op_sel_hi:[1,0]
	v_pk_mul_f32 v[112:113], v[112:113], v[138:139] op_sel_hi:[1,0]
	v_pk_mul_f32 v[106:107], v[106:107], v[138:139] op_sel_hi:[1,0]
	v_pk_mul_f32 v[108:109], v[108:109], v[138:139] op_sel_hi:[1,0]
	v_pk_mul_f32 v[166:167], v[110:111], v[110:111]
	v_pk_mul_f32 v[168:169], v[112:113], v[112:113]
	v_pk_mul_f32 v[170:171], v[106:107], v[106:107]
	v_pk_mul_f32 v[172:173], v[108:109], v[108:109]
	v_pk_fma_f32 v[166:167], v[144:145], v[166:167], v[146:147]
	v_pk_fma_f32 v[168:169], v[144:145], v[168:169], v[146:147]
	v_pk_fma_f32 v[170:171], v[144:145], v[170:171], v[146:147]
	v_pk_fma_f32 v[172:173], v[144:145], v[172:173], v[146:147]
	v_pk_mul_f32 v[166:167], v[110:111], v[166:167]
	v_pk_mul_f32 v[168:169], v[112:113], v[168:169]
	v_pk_mul_f32 v[170:171], v[106:107], v[170:171]
	v_pk_mul_f32 v[172:173], v[108:109], v[172:173]
	v_exp_f32_e32 v166, v166
	v_exp_f32_e32 v167, v167
	v_exp_f32_e32 v168, v168
	v_exp_f32_e32 v169, v169
	v_exp_f32_e32 v170, v170
	v_exp_f32_e32 v171, v171
	v_exp_f32_e32 v172, v172
	v_exp_f32_e32 v173, v173
	v_pk_add_f32 v[166:167], v[166:167], 1.0 op_sel_hi:[1,0]
	v_pk_add_f32 v[168:169], v[168:169], 1.0 op_sel_hi:[1,0]
	v_pk_add_f32 v[170:171], v[170:171], 1.0 op_sel_hi:[1,0]
	v_pk_add_f32 v[172:173], v[172:173], 1.0 op_sel_hi:[1,0]
	v_rcp_f32_e32 v166, v166
	v_rcp_f32_e32 v167, v167
	v_rcp_f32_e32 v168, v168
	v_rcp_f32_e32 v169, v169
	v_rcp_f32_e32 v170, v170
	v_rcp_f32_e32 v171, v171
	v_rcp_f32_e32 v172, v172
	v_rcp_f32_e32 v173, v173
	v_pk_mul_f32 v[110:111], v[110:111], v[166:167]
	v_pk_mul_f32 v[112:113], v[112:113], v[168:169]
	v_pk_mul_f32 v[106:107], v[106:107], v[170:171]
	v_pk_mul_f32 v[108:109], v[108:109], v[172:173]
	v_cvt_pk_bf16_f32 v110, v110, v111
	v_cvt_pk_bf16_f32 v111, v112, v113
	v_cvt_pk_bf16_f32 v112, v106, v107
	v_cvt_pk_bf16_f32 v113, v108, v109
	global_store_dwordx4 v141, v[110:113], s[56:57]
	v_pk_mul_f32 v[102:103], v[102:103], v[138:139] op_sel_hi:[1,0]
	v_pk_mul_f32 v[104:105], v[104:105], v[138:139] op_sel_hi:[1,0]
	v_pk_mul_f32 v[98:99], v[98:99], v[138:139] op_sel_hi:[1,0]
	v_pk_mul_f32 v[100:101], v[100:101], v[138:139] op_sel_hi:[1,0]
	v_pk_mul_f32 v[166:167], v[102:103], v[102:103]
	v_pk_mul_f32 v[168:169], v[104:105], v[104:105]
	v_pk_mul_f32 v[170:171], v[98:99], v[98:99]
	v_pk_mul_f32 v[172:173], v[100:101], v[100:101]
	v_pk_fma_f32 v[166:167], v[144:145], v[166:167], v[146:147]
	v_pk_fma_f32 v[168:169], v[144:145], v[168:169], v[146:147]
	v_pk_fma_f32 v[170:171], v[144:145], v[170:171], v[146:147]
	v_pk_fma_f32 v[172:173], v[144:145], v[172:173], v[146:147]
	v_pk_mul_f32 v[166:167], v[102:103], v[166:167]
	v_pk_mul_f32 v[168:169], v[104:105], v[168:169]
	v_pk_mul_f32 v[170:171], v[98:99], v[170:171]
	v_pk_mul_f32 v[172:173], v[100:101], v[172:173]
	v_exp_f32_e32 v166, v166
	v_exp_f32_e32 v167, v167
	v_exp_f32_e32 v168, v168
	v_exp_f32_e32 v169, v169
	v_exp_f32_e32 v170, v170
	v_exp_f32_e32 v171, v171
	v_exp_f32_e32 v172, v172
	v_exp_f32_e32 v173, v173
	v_pk_add_f32 v[166:167], v[166:167], 1.0 op_sel_hi:[1,0]
	v_pk_add_f32 v[168:169], v[168:169], 1.0 op_sel_hi:[1,0]
	v_pk_add_f32 v[170:171], v[170:171], 1.0 op_sel_hi:[1,0]
	v_pk_add_f32 v[172:173], v[172:173], 1.0 op_sel_hi:[1,0]
	v_rcp_f32_e32 v166, v166
	v_rcp_f32_e32 v167, v167
	v_rcp_f32_e32 v168, v168
	v_rcp_f32_e32 v169, v169
	v_rcp_f32_e32 v170, v170
	v_rcp_f32_e32 v171, v171
	v_rcp_f32_e32 v172, v172
	v_rcp_f32_e32 v173, v173
	v_pk_mul_f32 v[102:103], v[102:103], v[166:167]
	v_pk_mul_f32 v[104:105], v[104:105], v[168:169]
	v_pk_mul_f32 v[98:99], v[98:99], v[170:171]
	v_pk_mul_f32 v[100:101], v[100:101], v[172:173]
	v_cvt_pk_bf16_f32 v102, v102, v103
	v_cvt_pk_bf16_f32 v103, v104, v105
	v_cvt_pk_bf16_f32 v104, v98, v99
	v_cvt_pk_bf16_f32 v105, v100, v101
	global_store_dwordx4 v141, v[102:105], s[56:57] offset:256
	s_waitcnt lgkmcnt(5)
	v_mov_b32_e32 v138, v226
	v_add_u32_e32 v141, 0x34000, v140
	v_pk_mul_f32 v[94:95], v[94:95], v[138:139] op_sel_hi:[1,0]
	v_pk_mul_f32 v[96:97], v[96:97], v[138:139] op_sel_hi:[1,0]
	v_pk_mul_f32 v[90:91], v[90:91], v[138:139] op_sel_hi:[1,0]
	v_pk_mul_f32 v[92:93], v[92:93], v[138:139] op_sel_hi:[1,0]
	v_pk_mul_f32 v[166:167], v[94:95], v[94:95]
	v_pk_mul_f32 v[168:169], v[96:97], v[96:97]
	v_pk_mul_f32 v[170:171], v[90:91], v[90:91]
	v_pk_mul_f32 v[172:173], v[92:93], v[92:93]
	v_pk_fma_f32 v[166:167], v[144:145], v[166:167], v[146:147]
	v_pk_fma_f32 v[168:169], v[144:145], v[168:169], v[146:147]
	v_pk_fma_f32 v[170:171], v[144:145], v[170:171], v[146:147]
	v_pk_fma_f32 v[172:173], v[144:145], v[172:173], v[146:147]
	v_pk_mul_f32 v[166:167], v[94:95], v[166:167]
	v_pk_mul_f32 v[168:169], v[96:97], v[168:169]
	v_pk_mul_f32 v[170:171], v[90:91], v[170:171]
	v_pk_mul_f32 v[172:173], v[92:93], v[172:173]
	v_exp_f32_e32 v166, v166
	v_exp_f32_e32 v167, v167
	v_exp_f32_e32 v168, v168
	v_exp_f32_e32 v169, v169
	v_exp_f32_e32 v170, v170
	v_exp_f32_e32 v171, v171
	v_exp_f32_e32 v172, v172
	v_exp_f32_e32 v173, v173
	v_pk_add_f32 v[166:167], v[166:167], 1.0 op_sel_hi:[1,0]
	v_pk_add_f32 v[168:169], v[168:169], 1.0 op_sel_hi:[1,0]
	v_pk_add_f32 v[170:171], v[170:171], 1.0 op_sel_hi:[1,0]
	v_pk_add_f32 v[172:173], v[172:173], 1.0 op_sel_hi:[1,0]
	v_rcp_f32_e32 v166, v166
	v_rcp_f32_e32 v167, v167
	v_rcp_f32_e32 v168, v168
	v_rcp_f32_e32 v169, v169
	v_rcp_f32_e32 v170, v170
	v_rcp_f32_e32 v171, v171
	v_rcp_f32_e32 v172, v172
	v_rcp_f32_e32 v173, v173
	v_pk_mul_f32 v[94:95], v[94:95], v[166:167]
	v_pk_mul_f32 v[96:97], v[96:97], v[168:169]
	v_pk_mul_f32 v[90:91], v[90:91], v[170:171]
; __device__ __forceinline__ u32x4 pack8(const f32x4 a, const f32x4 b) { u32x4 w; w.x = cvt_pk_bf16(a[0], a[1]); w.y = cvt_pk_bf16(a[2], a[3]); w.z = cvt_pk_bf16(b[0], b[1]); w.w = cvt_pk_bf16(b[2], b[3]); return w; }
;     __device__ __forceinline__ void operator()(const f32x4 (&acc)[2][2][4][2], const Unit& u, int wr, int wc, int fr, int fq) const {
;     ...
;                 const int row = row0 + ai * 128 + m * 16; const float rs = (u.pm == pm0) ? RS[row & 255] : row_rstd(ss, row);
; #pragma unroll
;                 for (int bj = 0; bj < 2; ++bj) {
;                     f32x4 v[2], e[2];
; #pragma unroll
;                     for (int n = 0; n < 2; ++n) { v[n] = acc[ai][bj][m][n] * rs; e[n] = v[n] * ((v[n] * v[n]) * c3 + c1); }
;                     if (kind != 0) {
; #pragma unroll
;                         for (int n = 0; n < 2; ++n)
; #pragma unroll
;                             for (int j = 0; j < 4; ++j) e[n][j] = __builtin_amdgcn_exp2f(e[n][j]);
; #pragma unroll
;                         for (int n = 0; n < 2; ++n) e[n] = e[n] + 1.0f;
; #pragma unroll
;                         for (int n = 0; n < 2; ++n)
; #pragma unroll
;                             for (int j = 0; j < 4; ++j) e[n][j] = __builtin_amdgcn_rcpf(e[n][j]);
;                         if (kind == 1) { v[0] = v[0] * e[0]; v[1] = v[1] * e[1]; } else { v[0] = e[0]; v[1] = e[1]; }
;                     }
;                     __builtin_nontemporal_store(pack8(v[0], v[1]), (u32x4*)(base + (size_t)row * ld + col0 + bj * 128));
;                 }
	v_pk_mul_f32 v[92:93], v[92:93], v[172:173]
	v_cvt_pk_bf16_f32 v94, v94, v95
	v_cvt_pk_bf16_f32 v95, v96, v97
	v_cvt_pk_bf16_f32 v96, v90, v91
	v_cvt_pk_bf16_f32 v97, v92, v93
	global_store_dwordx4 v141, v[94:97], s[56:57]
	v_pk_mul_f32 v[86:87], v[86:87], v[138:139] op_sel_hi:[1,0]
	v_pk_mul_f32 v[88:89], v[88:89], v[138:139] op_sel_hi:[1,0]
	v_pk_mul_f32 v[82:83], v[82:83], v[138:139] op_sel_hi:[1,0]
	v_pk_mul_f32 v[84:85], v[84:85], v[138:139] op_sel_hi:[1,0]
	v_pk_mul_f32 v[166:167], v[86:87], v[86:87]
	v_pk_mul_f32 v[168:169], v[88:89], v[88:89]
	v_pk_mul_f32 v[170:171], v[82:83], v[82:83]
	v_pk_mul_f32 v[172:173], v[84:85], v[84:85]
	v_pk_fma_f32 v[166:167], v[144:145], v[166:167], v[146:147]
	v_pk_fma_f32 v[168:169], v[144:145], v[168:169], v[146:147]
	v_pk_fma_f32 v[170:171], v[144:145], v[170:171], v[146:147]
	v_pk_fma_f32 v[172:173], v[144:145], v[172:173], v[146:147]
	v_pk_mul_f32 v[166:167], v[86:87], v[166:167]
	v_pk_mul_f32 v[168:169], v[88:89], v[168:169]
	v_pk_mul_f32 v[170:171], v[82:83], v[170:171]
	v_pk_mul_f32 v[172:173], v[84:85], v[172:173]
	v_exp_f32_e32 v166, v166
	v_exp_f32_e32 v167, v167
	v_exp_f32_e32 v168, v168
	v_exp_f32_e32 v169, v169
	v_exp_f32_e32 v170, v170
	v_exp_f32_e32 v171, v171
	v_exp_f32_e32 v172, v172
	v_exp_f32_e32 v173, v173
	v_pk_add_f32 v[166:167], v[166:167], 1.0 op_sel_hi:[1,0]
	v_pk_add_f32 v[168:169], v[168:169], 1.0 op_sel_hi:[1,0]
	v_pk_add_f32 v[170:171], v[170:171], 1.0 op_sel_hi:[1,0]
	v_pk_add_f32 v[172:173], v[172:173], 1.0 op_sel_hi:[1,0]
	v_rcp_f32_e32 v166, v166
	v_rcp_f32_e32 v167, v167
	v_rcp_f32_e32 v168, v168
	v_rcp_f32_e32 v169, v169
	v_rcp_f32_e32 v170, v170
	v_rcp_f32_e32 v171, v171
	v_rcp_f32_e32 v172, v172
	v_rcp_f32_e32 v173, v173
	v_pk_mul_f32 v[86:87], v[86:87], v[166:167]
	v_pk_mul_f32 v[88:89], v[88:89], v[168:169]
	v_pk_mul_f32 v[82:83], v[82:83], v[170:171]
	v_pk_mul_f32 v[84:85], v[84:85], v[172:173]
	v_cvt_pk_bf16_f32 v86, v86, v87
	v_cvt_pk_bf16_f32 v87, v88, v89
	v_cvt_pk_bf16_f32 v88, v82, v83
	v_cvt_pk_bf16_f32 v89, v84, v85
	global_store_dwordx4 v141, v[86:89], s[56:57] offset:256
	s_waitcnt lgkmcnt(4)
	v_mov_b32_e32 v138, v227
	v_add_u32_e32 v141, 0x4e000, v140
	v_pk_mul_f32 v[78:79], v[78:79], v[138:139] op_sel_hi:[1,0]
	v_pk_mul_f32 v[80:81], v[80:81], v[138:139] op_sel_hi:[1,0]
	v_pk_mul_f32 v[74:75], v[74:75], v[138:139] op_sel_hi:[1,0]
	v_pk_mul_f32 v[76:77], v[76:77], v[138:139] op_sel_hi:[1,0]
	v_pk_mul_f32 v[166:167], v[78:79], v[78:79]
	v_pk_mul_f32 v[168:169], v[80:81], v[80:81]
	v_pk_mul_f32 v[170:171], v[74:75], v[74:75]
	v_pk_mul_f32 v[172:173], v[76:77], v[76:77]
	v_pk_fma_f32 v[166:167], v[144:145], v[166:167], v[146:147]
	v_pk_fma_f32 v[168:169], v[144:145], v[168:169], v[146:147]
	v_pk_fma_f32 v[170:171], v[144:145], v[170:171], v[146:147]
	v_pk_fma_f32 v[172:173], v[144:145], v[172:173], v[146:147]
	v_pk_mul_f32 v[166:167], v[78:79], v[166:167]
	v_pk_mul_f32 v[168:169], v[80:81], v[168:169]
	v_pk_mul_f32 v[170:171], v[74:75], v[170:171]
	v_pk_mul_f32 v[172:173], v[76:77], v[172:173]
	v_exp_f32_e32 v166, v166
	v_exp_f32_e32 v167, v167
	v_exp_f32_e32 v168, v168
	v_exp_f32_e32 v169, v169
	v_exp_f32_e32 v170, v170
	v_exp_f32_e32 v171, v171
	v_exp_f32_e32 v172, v172
	v_exp_f32_e32 v173, v173
	v_pk_add_f32 v[166:167], v[166:167], 1.0 op_sel_hi:[1,0]
	v_pk_add_f32 v[168:169], v[168:169], 1.0 op_sel_hi:[1,0]
	v_pk_add_f32 v[170:171], v[170:171], 1.0 op_sel_hi:[1,0]
	v_pk_add_f32 v[172:173], v[172:173], 1.0 op_sel_hi:[1,0]
	v_rcp_f32_e32 v166, v166
	v_rcp_f32_e32 v167, v167
	v_rcp_f32_e32 v168, v168
	v_rcp_f32_e32 v169, v169
	v_rcp_f32_e32 v170, v170
	v_rcp_f32_e32 v171, v171
	v_rcp_f32_e32 v172, v172
	v_rcp_f32_e32 v173, v173
	v_pk_mul_f32 v[78:79], v[78:79], v[166:167]
	v_pk_mul_f32 v[80:81], v[80:81], v[168:169]
	v_pk_mul_f32 v[74:75], v[74:75], v[170:171]
	v_pk_mul_f32 v[76:77], v[76:77], v[172:173]
	v_cvt_pk_bf16_f32 v78, v78, v79
	v_cvt_pk_bf16_f32 v79, v80, v81
	v_cvt_pk_bf16_f32 v80, v74, v75
	v_cvt_pk_bf16_f32 v81, v76, v77
	global_store_dwordx4 v141, v[78:81], s[56:57]
	v_pk_mul_f32 v[70:71], v[70:71], v[138:139] op_sel_hi:[1,0]
	v_pk_mul_f32 v[72:73], v[72:73], v[138:139] op_sel_hi:[1,0]
	v_pk_mul_f32 v[66:67], v[66:67], v[138:139] op_sel_hi:[1,0]
	v_pk_mul_f32 v[68:69], v[68:69], v[138:139] op_sel_hi:[1,0]
	v_pk_mul_f32 v[166:167], v[70:71], v[70:71]
	v_pk_mul_f32 v[168:169], v[72:73], v[72:73]
	v_pk_mul_f32 v[170:171], v[66:67], v[66:67]
	v_pk_mul_f32 v[172:173], v[68:69], v[68:69]
	v_pk_fma_f32 v[166:167], v[144:145], v[166:167], v[146:147]
	v_pk_fma_f32 v[168:169], v[144:145], v[168:169], v[146:147]
	v_pk_fma_f32 v[170:171], v[144:145], v[170:171], v[146:147]
	v_pk_fma_f32 v[172:173], v[144:145], v[172:173], v[146:147]
	v_pk_mul_f32 v[166:167], v[70:71], v[166:167]
	v_pk_mul_f32 v[168:169], v[72:73], v[168:169]
	v_pk_mul_f32 v[170:171], v[66:67], v[170:171]
	v_pk_mul_f32 v[172:173], v[68:69], v[172:173]
	v_exp_f32_e32 v166, v166
	v_exp_f32_e32 v167, v167
	v_exp_f32_e32 v168, v168
	v_exp_f32_e32 v169, v169
	v_exp_f32_e32 v170, v170
	v_exp_f32_e32 v171, v171
	v_exp_f32_e32 v172, v172
	v_exp_f32_e32 v173, v173
	v_pk_add_f32 v[166:167], v[166:167], 1.0 op_sel_hi:[1,0]
	v_pk_add_f32 v[168:169], v[168:169], 1.0 op_sel_hi:[1,0]
	v_pk_add_f32 v[170:171], v[170:171], 1.0 op_sel_hi:[1,0]
	v_pk_add_f32 v[172:173], v[172:173], 1.0 op_sel_hi:[1,0]
	v_rcp_f32_e32 v166, v166
	v_rcp_f32_e32 v167, v167
	v_rcp_f32_e32 v168, v168
	v_rcp_f32_e32 v169, v169
	v_rcp_f32_e32 v170, v170
	v_rcp_f32_e32 v171, v171
	v_rcp_f32_e32 v172, v172
	v_rcp_f32_e32 v173, v173
	v_pk_mul_f32 v[70:71], v[70:71], v[166:167]
	v_pk_mul_f32 v[72:73], v[72:73], v[168:169]
	v_pk_mul_f32 v[66:67], v[66:67], v[170:171]
	v_pk_mul_f32 v[68:69], v[68:69], v[172:173]
	v_cvt_pk_bf16_f32 v70, v70, v71
	v_cvt_pk_bf16_f32 v71, v72, v73
	v_cvt_pk_bf16_f32 v72, v66, v67
	v_cvt_pk_bf16_f32 v73, v68, v69
	global_store_dwordx4 v141, v[70:73], s[56:57] offset:256
	s_waitcnt lgkmcnt(3)
; __device__ __forceinline__ u32x4 pack8(const f32x4 a, const f32x4 b) { u32x4 w; w.x = cvt_pk_bf16(a[0], a[1]); w.y = cvt_pk_bf16(a[2], a[3]); w.z = cvt_pk_bf16(b[0], b[1]); w.w = cvt_pk_bf16(b[2], b[3]); return w; }
;     __device__ __forceinline__ void operator()(const f32x4 (&acc)[2][2][4][2], const Unit& u, int wr, int wc, int fr, int fq) const {
;     ...
;                 const int row = row0 + ai * 128 + m * 16; const float rs = (u.pm == pm0) ? RS[row & 255] : row_rstd(ss, row);
; #pragma unroll
;                 for (int bj = 0; bj < 2; ++bj) {
;                     f32x4 v[2], e[2];
; #pragma unroll
;                     for (int n = 0; n < 2; ++n) { v[n] = acc[ai][bj][m][n] * rs; e[n] = v[n] * ((v[n] * v[n]) * c3 + c1); }
;                     if (kind != 0) {
; #pragma unroll
;                         for (int n = 0; n < 2; ++n)
; #pragma unroll
;                             for (int j = 0; j < 4; ++j) e[n][j] = __builtin_amdgcn_exp2f(e[n][j]);
; #pragma unroll
;                         for (int n = 0; n < 2; ++n) e[n] = e[n] + 1.0f;
; #pragma unroll
;                         for (int n = 0; n < 2; ++n)
; #pragma unroll
;                             for (int j = 0; j < 4; ++j) e[n][j] = __builtin_amdgcn_rcpf(e[n][j]);
;                         if (kind == 1) { v[0] = v[0] * e[0]; v[1] = v[1] * e[1]; } else { v[0] = e[0]; v[1] = e[1]; }
;                     }
;                     __builtin_nontemporal_store(pack8(v[0], v[1]), (u32x4*)(base + (size_t)row * ld + col0 + bj * 128));
;                 }
	v_mov_b32_e32 v138, v228
	v_add_u32_e32 v141, 0xd0000, v140
	v_pk_mul_f32 v[62:63], v[62:63], v[138:139] op_sel_hi:[1,0]
	v_pk_mul_f32 v[64:65], v[64:65], v[138:139] op_sel_hi:[1,0]
	v_pk_mul_f32 v[58:59], v[58:59], v[138:139] op_sel_hi:[1,0]
	v_pk_mul_f32 v[60:61], v[60:61], v[138:139] op_sel_hi:[1,0]
	v_pk_mul_f32 v[166:167], v[62:63], v[62:63]
	v_pk_mul_f32 v[168:169], v[64:65], v[64:65]
	v_pk_mul_f32 v[170:171], v[58:59], v[58:59]
	v_pk_mul_f32 v[172:173], v[60:61], v[60:61]
	v_pk_fma_f32 v[166:167], v[144:145], v[166:167], v[146:147]
	v_pk_fma_f32 v[168:169], v[144:145], v[168:169], v[146:147]
	v_pk_fma_f32 v[170:171], v[144:145], v[170:171], v[146:147]
	v_pk_fma_f32 v[172:173], v[144:145], v[172:173], v[146:147]
	v_pk_mul_f32 v[166:167], v[62:63], v[166:167]
	v_pk_mul_f32 v[168:169], v[64:65], v[168:169]
	v_pk_mul_f32 v[170:171], v[58:59], v[170:171]
	v_pk_mul_f32 v[172:173], v[60:61], v[172:173]
	v_exp_f32_e32 v166, v166
	v_exp_f32_e32 v167, v167
	v_exp_f32_e32 v168, v168
	v_exp_f32_e32 v169, v169
	v_exp_f32_e32 v170, v170
	v_exp_f32_e32 v171, v171
	v_exp_f32_e32 v172, v172
	v_exp_f32_e32 v173, v173
	v_pk_add_f32 v[166:167], v[166:167], 1.0 op_sel_hi:[1,0]
	v_pk_add_f32 v[168:169], v[168:169], 1.0 op_sel_hi:[1,0]
	v_pk_add_f32 v[170:171], v[170:171], 1.0 op_sel_hi:[1,0]
	v_pk_add_f32 v[172:173], v[172:173], 1.0 op_sel_hi:[1,0]
	v_rcp_f32_e32 v166, v166
	v_rcp_f32_e32 v167, v167
	v_rcp_f32_e32 v168, v168
	v_rcp_f32_e32 v169, v169
	v_rcp_f32_e32 v170, v170
	v_rcp_f32_e32 v171, v171
	v_rcp_f32_e32 v172, v172
	v_rcp_f32_e32 v173, v173
	v_pk_mul_f32 v[62:63], v[62:63], v[166:167]
	v_pk_mul_f32 v[64:65], v[64:65], v[168:169]
	v_pk_mul_f32 v[58:59], v[58:59], v[170:171]
	v_pk_mul_f32 v[60:61], v[60:61], v[172:173]
	v_cvt_pk_bf16_f32 v62, v62, v63
	v_cvt_pk_bf16_f32 v63, v64, v65
	v_cvt_pk_bf16_f32 v64, v58, v59
	v_cvt_pk_bf16_f32 v65, v60, v61
	global_store_dwordx4 v141, v[62:65], s[56:57]
	v_pk_mul_f32 v[54:55], v[54:55], v[138:139] op_sel_hi:[1,0]
	v_pk_mul_f32 v[56:57], v[56:57], v[138:139] op_sel_hi:[1,0]
	v_pk_mul_f32 v[50:51], v[50:51], v[138:139] op_sel_hi:[1,0]
	v_pk_mul_f32 v[52:53], v[52:53], v[138:139] op_sel_hi:[1,0]
	v_pk_mul_f32 v[166:167], v[54:55], v[54:55]
	v_pk_mul_f32 v[168:169], v[56:57], v[56:57]
	v_pk_mul_f32 v[170:171], v[50:51], v[50:51]
	v_pk_mul_f32 v[172:173], v[52:53], v[52:53]
	v_pk_fma_f32 v[166:167], v[144:145], v[166:167], v[146:147]
	v_pk_fma_f32 v[168:169], v[144:145], v[168:169], v[146:147]
	v_pk_fma_f32 v[170:171], v[144:145], v[170:171], v[146:147]
	v_pk_fma_f32 v[172:173], v[144:145], v[172:173], v[146:147]
	v_pk_mul_f32 v[166:167], v[54:55], v[166:167]
	v_pk_mul_f32 v[168:169], v[56:57], v[168:169]
	v_pk_mul_f32 v[170:171], v[50:51], v[170:171]
	v_pk_mul_f32 v[172:173], v[52:53], v[172:173]
	v_exp_f32_e32 v166, v166
	v_exp_f32_e32 v167, v167
	v_exp_f32_e32 v168, v168
	v_exp_f32_e32 v169, v169
	v_exp_f32_e32 v170, v170
	v_exp_f32_e32 v171, v171
	v_exp_f32_e32 v172, v172
	v_exp_f32_e32 v173, v173
	v_pk_add_f32 v[166:167], v[166:167], 1.0 op_sel_hi:[1,0]
	v_pk_add_f32 v[168:169], v[168:169], 1.0 op_sel_hi:[1,0]
	v_pk_add_f32 v[170:171], v[170:171], 1.0 op_sel_hi:[1,0]
	v_pk_add_f32 v[172:173], v[172:173], 1.0 op_sel_hi:[1,0]
	v_rcp_f32_e32 v166, v166
	v_rcp_f32_e32 v167, v167
	v_rcp_f32_e32 v168, v168
	v_rcp_f32_e32 v169, v169
	v_rcp_f32_e32 v170, v170
	v_rcp_f32_e32 v171, v171
	v_rcp_f32_e32 v172, v172
	v_rcp_f32_e32 v173, v173
	v_pk_mul_f32 v[54:55], v[54:55], v[166:167]
	v_pk_mul_f32 v[56:57], v[56:57], v[168:169]
	v_pk_mul_f32 v[50:51], v[50:51], v[170:171]
	v_pk_mul_f32 v[52:53], v[52:53], v[172:173]
	v_cvt_pk_bf16_f32 v54, v54, v55
	v_cvt_pk_bf16_f32 v55, v56, v57
	v_cvt_pk_bf16_f32 v56, v50, v51
	v_cvt_pk_bf16_f32 v57, v52, v53
	global_store_dwordx4 v141, v[54:57], s[56:57] offset:256
	s_waitcnt lgkmcnt(2)
	v_mov_b32_e32 v138, v229
	v_add_u32_e32 v141, 0xea000, v140
	v_pk_mul_f32 v[46:47], v[46:47], v[138:139] op_sel_hi:[1,0]
	v_pk_mul_f32 v[48:49], v[48:49], v[138:139] op_sel_hi:[1,0]
	v_pk_mul_f32 v[42:43], v[42:43], v[138:139] op_sel_hi:[1,0]
	v_pk_mul_f32 v[44:45], v[44:45], v[138:139] op_sel_hi:[1,0]
	v_pk_mul_f32 v[166:167], v[46:47], v[46:47]
	v_pk_mul_f32 v[168:169], v[48:49], v[48:49]
	v_pk_mul_f32 v[170:171], v[42:43], v[42:43]
	v_pk_mul_f32 v[172:173], v[44:45], v[44:45]
	v_pk_fma_f32 v[166:167], v[144:145], v[166:167], v[146:147]
	v_pk_fma_f32 v[168:169], v[144:145], v[168:169], v[146:147]
	v_pk_fma_f32 v[170:171], v[144:145], v[170:171], v[146:147]
	v_pk_fma_f32 v[172:173], v[144:145], v[172:173], v[146:147]
	v_pk_mul_f32 v[166:167], v[46:47], v[166:167]
	v_pk_mul_f32 v[168:169], v[48:49], v[168:169]
	v_pk_mul_f32 v[170:171], v[42:43], v[170:171]
	v_pk_mul_f32 v[172:173], v[44:45], v[172:173]
	v_exp_f32_e32 v166, v166
	v_exp_f32_e32 v167, v167
	v_exp_f32_e32 v168, v168
	v_exp_f32_e32 v169, v169
	v_exp_f32_e32 v170, v170
	v_exp_f32_e32 v171, v171
	v_exp_f32_e32 v172, v172
	v_exp_f32_e32 v173, v173
	v_pk_add_f32 v[166:167], v[166:167], 1.0 op_sel_hi:[1,0]
	v_pk_add_f32 v[168:169], v[168:169], 1.0 op_sel_hi:[1,0]
	v_pk_add_f32 v[170:171], v[170:171], 1.0 op_sel_hi:[1,0]
	v_pk_add_f32 v[172:173], v[172:173], 1.0 op_sel_hi:[1,0]
	v_rcp_f32_e32 v166, v166
	v_rcp_f32_e32 v167, v167
	v_rcp_f32_e32 v168, v168
	v_rcp_f32_e32 v169, v169
	v_rcp_f32_e32 v170, v170
	v_rcp_f32_e32 v171, v171
	v_rcp_f32_e32 v172, v172
	v_rcp_f32_e32 v173, v173
	v_pk_mul_f32 v[46:47], v[46:47], v[166:167]
	v_pk_mul_f32 v[48:49], v[48:49], v[168:169]
	v_pk_mul_f32 v[42:43], v[42:43], v[170:171]
	v_pk_mul_f32 v[44:45], v[44:45], v[172:173]
	v_cvt_pk_bf16_f32 v46, v46, v47
	v_cvt_pk_bf16_f32 v47, v48, v49
; __device__ __forceinline__ u32x4 pack8(const f32x4 a, const f32x4 b) { u32x4 w; w.x = cvt_pk_bf16(a[0], a[1]); w.y = cvt_pk_bf16(a[2], a[3]); w.z = cvt_pk_bf16(b[0], b[1]); w.w = cvt_pk_bf16(b[2], b[3]); return w; }
;     __device__ __forceinline__ void operator()(const f32x4 (&acc)[2][2][4][2], const Unit& u, int wr, int wc, int fr, int fq) const {
;     ...
;                 const int row = row0 + ai * 128 + m * 16; const float rs = (u.pm == pm0) ? RS[row & 255] : row_rstd(ss, row);
; #pragma unroll
;                 for (int bj = 0; bj < 2; ++bj) {
;                     f32x4 v[2], e[2];
; #pragma unroll
;                     for (int n = 0; n < 2; ++n) { v[n] = acc[ai][bj][m][n] * rs; e[n] = v[n] * ((v[n] * v[n]) * c3 + c1); }
;                     if (kind != 0) {
; #pragma unroll
;                         for (int n = 0; n < 2; ++n)
; #pragma unroll
;                             for (int j = 0; j < 4; ++j) e[n][j] = __builtin_amdgcn_exp2f(e[n][j]);
; #pragma unroll
;                         for (int n = 0; n < 2; ++n) e[n] = e[n] + 1.0f;
; #pragma unroll
;                         for (int n = 0; n < 2; ++n)
; #pragma unroll
;                             for (int j = 0; j < 4; ++j) e[n][j] = __builtin_amdgcn_rcpf(e[n][j]);
;                         if (kind == 1) { v[0] = v[0] * e[0]; v[1] = v[1] * e[1]; } else { v[0] = e[0]; v[1] = e[1]; }
;                     }
;                     __builtin_nontemporal_store(pack8(v[0], v[1]), (u32x4*)(base + (size_t)row * ld + col0 + bj * 128));
;                 }
	v_cvt_pk_bf16_f32 v48, v42, v43
	v_cvt_pk_bf16_f32 v49, v44, v45
	global_store_dwordx4 v141, v[46:49], s[56:57]
	v_pk_mul_f32 v[38:39], v[38:39], v[138:139] op_sel_hi:[1,0]
	v_pk_mul_f32 v[40:41], v[40:41], v[138:139] op_sel_hi:[1,0]
	v_pk_mul_f32 v[34:35], v[34:35], v[138:139] op_sel_hi:[1,0]
	v_pk_mul_f32 v[36:37], v[36:37], v[138:139] op_sel_hi:[1,0]
	v_pk_mul_f32 v[166:167], v[38:39], v[38:39]
	v_pk_mul_f32 v[168:169], v[40:41], v[40:41]
	v_pk_mul_f32 v[170:171], v[34:35], v[34:35]
	v_pk_mul_f32 v[172:173], v[36:37], v[36:37]
	v_pk_fma_f32 v[166:167], v[144:145], v[166:167], v[146:147]
	v_pk_fma_f32 v[168:169], v[144:145], v[168:169], v[146:147]
	v_pk_fma_f32 v[170:171], v[144:145], v[170:171], v[146:147]
	v_pk_fma_f32 v[172:173], v[144:145], v[172:173], v[146:147]
	v_pk_mul_f32 v[166:167], v[38:39], v[166:167]
	v_pk_mul_f32 v[168:169], v[40:41], v[168:169]
	v_pk_mul_f32 v[170:171], v[34:35], v[170:171]
	v_pk_mul_f32 v[172:173], v[36:37], v[172:173]
	v_exp_f32_e32 v166, v166
	v_exp_f32_e32 v167, v167
	v_exp_f32_e32 v168, v168
	v_exp_f32_e32 v169, v169
	v_exp_f32_e32 v170, v170
	v_exp_f32_e32 v171, v171
	v_exp_f32_e32 v172, v172
	v_exp_f32_e32 v173, v173
	v_pk_add_f32 v[166:167], v[166:167], 1.0 op_sel_hi:[1,0]
	v_pk_add_f32 v[168:169], v[168:169], 1.0 op_sel_hi:[1,0]
	v_pk_add_f32 v[170:171], v[170:171], 1.0 op_sel_hi:[1,0]
	v_pk_add_f32 v[172:173], v[172:173], 1.0 op_sel_hi:[1,0]
	v_rcp_f32_e32 v166, v166
	v_rcp_f32_e32 v167, v167
	v_rcp_f32_e32 v168, v168
	v_rcp_f32_e32 v169, v169
	v_rcp_f32_e32 v170, v170
	v_rcp_f32_e32 v171, v171
	v_rcp_f32_e32 v172, v172
	v_rcp_f32_e32 v173, v173
	v_pk_mul_f32 v[38:39], v[38:39], v[166:167]
	v_pk_mul_f32 v[40:41], v[40:41], v[168:169]
	v_pk_mul_f32 v[34:35], v[34:35], v[170:171]
	v_pk_mul_f32 v[36:37], v[36:37], v[172:173]
	v_cvt_pk_bf16_f32 v38, v38, v39
	v_cvt_pk_bf16_f32 v39, v40, v41
	v_cvt_pk_bf16_f32 v40, v34, v35
	v_cvt_pk_bf16_f32 v41, v36, v37
	global_store_dwordx4 v141, v[38:41], s[56:57] offset:256
	s_waitcnt lgkmcnt(1)
	v_mov_b32_e32 v138, v230
	v_add_u32_e32 v141, 0x104000, v140
	v_pk_mul_f32 v[30:31], v[30:31], v[138:139] op_sel_hi:[1,0]
	v_pk_mul_f32 v[32:33], v[32:33], v[138:139] op_sel_hi:[1,0]
	v_pk_mul_f32 v[26:27], v[26:27], v[138:139] op_sel_hi:[1,0]
	v_pk_mul_f32 v[28:29], v[28:29], v[138:139] op_sel_hi:[1,0]
	v_pk_mul_f32 v[166:167], v[30:31], v[30:31]
	v_pk_mul_f32 v[168:169], v[32:33], v[32:33]
	v_pk_mul_f32 v[170:171], v[26:27], v[26:27]
	v_pk_mul_f32 v[172:173], v[28:29], v[28:29]
	v_pk_fma_f32 v[166:167], v[144:145], v[166:167], v[146:147]
	v_pk_fma_f32 v[168:169], v[144:145], v[168:169], v[146:147]
	v_pk_fma_f32 v[170:171], v[144:145], v[170:171], v[146:147]
	v_pk_fma_f32 v[172:173], v[144:145], v[172:173], v[146:147]
	v_pk_mul_f32 v[166:167], v[30:31], v[166:167]
	v_pk_mul_f32 v[168:169], v[32:33], v[168:169]
	v_pk_mul_f32 v[170:171], v[26:27], v[170:171]
	v_pk_mul_f32 v[172:173], v[28:29], v[172:173]
	v_exp_f32_e32 v166, v166
	v_exp_f32_e32 v167, v167
	v_exp_f32_e32 v168, v168
	v_exp_f32_e32 v169, v169
	v_exp_f32_e32 v170, v170
	v_exp_f32_e32 v171, v171
	v_exp_f32_e32 v172, v172
	v_exp_f32_e32 v173, v173
	v_pk_add_f32 v[166:167], v[166:167], 1.0 op_sel_hi:[1,0]
	v_pk_add_f32 v[168:169], v[168:169], 1.0 op_sel_hi:[1,0]
	v_pk_add_f32 v[170:171], v[170:171], 1.0 op_sel_hi:[1,0]
	v_pk_add_f32 v[172:173], v[172:173], 1.0 op_sel_hi:[1,0]
	v_rcp_f32_e32 v166, v166
	v_rcp_f32_e32 v167, v167
	v_rcp_f32_e32 v168, v168
	v_rcp_f32_e32 v169, v169
	v_rcp_f32_e32 v170, v170
	v_rcp_f32_e32 v171, v171
	v_rcp_f32_e32 v172, v172
	v_rcp_f32_e32 v173, v173
	v_pk_mul_f32 v[30:31], v[30:31], v[166:167]
	v_pk_mul_f32 v[32:33], v[32:33], v[168:169]
	v_pk_mul_f32 v[26:27], v[26:27], v[170:171]
	v_pk_mul_f32 v[28:29], v[28:29], v[172:173]
	v_cvt_pk_bf16_f32 v30, v30, v31
	v_cvt_pk_bf16_f32 v31, v32, v33
	v_cvt_pk_bf16_f32 v32, v26, v27
	v_cvt_pk_bf16_f32 v33, v28, v29
	global_store_dwordx4 v141, v[30:33], s[56:57]
	v_pk_mul_f32 v[22:23], v[22:23], v[138:139] op_sel_hi:[1,0]
	v_pk_mul_f32 v[24:25], v[24:25], v[138:139] op_sel_hi:[1,0]
	v_pk_mul_f32 v[18:19], v[18:19], v[138:139] op_sel_hi:[1,0]
	v_pk_mul_f32 v[20:21], v[20:21], v[138:139] op_sel_hi:[1,0]
	v_pk_mul_f32 v[166:167], v[22:23], v[22:23]
	v_pk_mul_f32 v[168:169], v[24:25], v[24:25]
	v_pk_mul_f32 v[170:171], v[18:19], v[18:19]
	v_pk_mul_f32 v[172:173], v[20:21], v[20:21]
	v_pk_fma_f32 v[166:167], v[144:145], v[166:167], v[146:147]
	v_pk_fma_f32 v[168:169], v[144:145], v[168:169], v[146:147]
	v_pk_fma_f32 v[170:171], v[144:145], v[170:171], v[146:147]
	v_pk_fma_f32 v[172:173], v[144:145], v[172:173], v[146:147]
	v_pk_mul_f32 v[166:167], v[22:23], v[166:167]
	v_pk_mul_f32 v[168:169], v[24:25], v[168:169]
	v_pk_mul_f32 v[170:171], v[18:19], v[170:171]
	v_pk_mul_f32 v[172:173], v[20:21], v[172:173]
	v_exp_f32_e32 v166, v166
	v_exp_f32_e32 v167, v167
	v_exp_f32_e32 v168, v168
	v_exp_f32_e32 v169, v169
	v_exp_f32_e32 v170, v170
	v_exp_f32_e32 v171, v171
	v_exp_f32_e32 v172, v172
	v_exp_f32_e32 v173, v173
	v_pk_add_f32 v[166:167], v[166:167], 1.0 op_sel_hi:[1,0]
	v_pk_add_f32 v[168:169], v[168:169], 1.0 op_sel_hi:[1,0]
	v_pk_add_f32 v[170:171], v[170:171], 1.0 op_sel_hi:[1,0]
	v_pk_add_f32 v[172:173], v[172:173], 1.0 op_sel_hi:[1,0]
	v_rcp_f32_e32 v166, v166
	v_rcp_f32_e32 v167, v167
	v_rcp_f32_e32 v168, v168
	v_rcp_f32_e32 v169, v169
	v_rcp_f32_e32 v170, v170
	v_rcp_f32_e32 v171, v171
	v_rcp_f32_e32 v172, v172
	v_rcp_f32_e32 v173, v173
	v_pk_mul_f32 v[22:23], v[22:23], v[166:167]
	v_pk_mul_f32 v[24:25], v[24:25], v[168:169]
	v_pk_mul_f32 v[18:19], v[18:19], v[170:171]
	v_pk_mul_f32 v[20:21], v[20:21], v[172:173]
	v_cvt_pk_bf16_f32 v22, v22, v23
	v_cvt_pk_bf16_f32 v23, v24, v25
	v_cvt_pk_bf16_f32 v24, v18, v19
	v_cvt_pk_bf16_f32 v25, v20, v21
	global_store_dwordx4 v141, v[22:25], s[56:57] offset:256
	s_waitcnt lgkmcnt(0)
; __device__ __forceinline__ u32x4 pack8(const f32x4 a, const f32x4 b) { u32x4 w; w.x = cvt_pk_bf16(a[0], a[1]); w.y = cvt_pk_bf16(a[2], a[3]); w.z = cvt_pk_bf16(b[0], b[1]); w.w = cvt_pk_bf16(b[2], b[3]); return w; }
;     __device__ __forceinline__ void operator()(const f32x4 (&acc)[2][2][4][2], const Unit& u, int wr, int wc, int fr, int fq) const {
;     ...
;         bf16_t* base = kind == 0 ? P1 : P2; const int ld = kind == 0 ? P1W : P2W; const int col0 = (kind == 0 ? u.pn : u.pn - 7) * 256 + wc * 32 + 8 * fq;
;         const float c3 = kind == 1 ? -LOG2E_ * 1.5957691216f * 0.044715f : 0.f, c1 = kind == 1 ? -LOG2E_ * 1.5957691216f : -LOG2E_;
; #pragma unroll
;         for (int ai = 0; ai < 2; ++ai)
; #pragma unroll
;             for (int m = 0; m < 4; ++m) {
;                 const int row = row0 + ai * 128 + m * 16; const float rs = (u.pm == pm0) ? RS[row & 255] : row_rstd(ss, row);
; #pragma unroll
;                 for (int bj = 0; bj < 2; ++bj) {
;                     f32x4 v[2], e[2];
; #pragma unroll
;                     for (int n = 0; n < 2; ++n) { v[n] = acc[ai][bj][m][n] * rs; e[n] = v[n] * ((v[n] * v[n]) * c3 + c1); }
;                     if (kind != 0) {
; #pragma unroll
;                         for (int n = 0; n < 2; ++n)
; #pragma unroll
;                             for (int j = 0; j < 4; ++j) e[n][j] = __builtin_amdgcn_exp2f(e[n][j]);
; #pragma unroll
;                         for (int n = 0; n < 2; ++n) e[n] = e[n] + 1.0f;
; #pragma unroll
;                         for (int n = 0; n < 2; ++n)
; #pragma unroll
;                             for (int j = 0; j < 4; ++j) e[n][j] = __builtin_amdgcn_rcpf(e[n][j]);
;                         if (kind == 1) { v[0] = v[0] * e[0]; v[1] = v[1] * e[1]; } else { v[0] = e[0]; v[1] = e[1]; }
;                     }
;                     __builtin_nontemporal_store(pack8(v[0], v[1]), (u32x4*)(base + (size_t)row * ld + col0 + bj * 128));
;                 }
	v_mov_b32_e32 v138, v231
	v_add_u32_e32 v141, 0x11e000, v140
	v_pk_mul_f32 v[14:15], v[14:15], v[138:139] op_sel_hi:[1,0]
	v_pk_mul_f32 v[16:17], v[16:17], v[138:139] op_sel_hi:[1,0]
	v_pk_mul_f32 v[10:11], v[10:11], v[138:139] op_sel_hi:[1,0]
	v_pk_mul_f32 v[12:13], v[12:13], v[138:139] op_sel_hi:[1,0]
	v_pk_mul_f32 v[166:167], v[14:15], v[14:15]
	v_pk_mul_f32 v[168:169], v[16:17], v[16:17]
	v_pk_mul_f32 v[170:171], v[10:11], v[10:11]
	v_pk_mul_f32 v[172:173], v[12:13], v[12:13]
	v_pk_fma_f32 v[166:167], v[144:145], v[166:167], v[146:147]
	v_pk_fma_f32 v[168:169], v[144:145], v[168:169], v[146:147]
	v_pk_fma_f32 v[170:171], v[144:145], v[170:171], v[146:147]
	v_pk_fma_f32 v[172:173], v[144:145], v[172:173], v[146:147]
	v_pk_mul_f32 v[166:167], v[14:15], v[166:167]
	v_pk_mul_f32 v[168:169], v[16:17], v[168:169]
	v_pk_mul_f32 v[170:171], v[10:11], v[170:171]
	v_pk_mul_f32 v[172:173], v[12:13], v[172:173]
	v_exp_f32_e32 v166, v166
	v_exp_f32_e32 v167, v167
	v_exp_f32_e32 v168, v168
	v_exp_f32_e32 v169, v169
	v_exp_f32_e32 v170, v170
	v_exp_f32_e32 v171, v171
	v_exp_f32_e32 v172, v172
	v_exp_f32_e32 v173, v173
	v_pk_add_f32 v[166:167], v[166:167], 1.0 op_sel_hi:[1,0]
	v_pk_add_f32 v[168:169], v[168:169], 1.0 op_sel_hi:[1,0]
	v_pk_add_f32 v[170:171], v[170:171], 1.0 op_sel_hi:[1,0]
	v_pk_add_f32 v[172:173], v[172:173], 1.0 op_sel_hi:[1,0]
	v_rcp_f32_e32 v166, v166
	v_rcp_f32_e32 v167, v167
	v_rcp_f32_e32 v168, v168
	v_rcp_f32_e32 v169, v169
	v_rcp_f32_e32 v170, v170
	v_rcp_f32_e32 v171, v171
	v_rcp_f32_e32 v172, v172
	v_rcp_f32_e32 v173, v173
	v_pk_mul_f32 v[14:15], v[14:15], v[166:167]
	v_pk_mul_f32 v[16:17], v[16:17], v[168:169]
	v_pk_mul_f32 v[10:11], v[10:11], v[170:171]
	v_pk_mul_f32 v[12:13], v[12:13], v[172:173]
	v_cvt_pk_bf16_f32 v14, v14, v15
	v_cvt_pk_bf16_f32 v15, v16, v17
	v_cvt_pk_bf16_f32 v16, v10, v11
	v_cvt_pk_bf16_f32 v17, v12, v13
	global_store_dwordx4 v141, v[14:17], s[56:57]
	v_pk_mul_f32 v[6:7], v[6:7], v[138:139] op_sel_hi:[1,0]
	v_pk_mul_f32 v[8:9], v[8:9], v[138:139] op_sel_hi:[1,0]
	v_pk_mul_f32 v[2:3], v[2:3], v[138:139] op_sel_hi:[1,0]
	v_pk_mul_f32 v[4:5], v[4:5], v[138:139] op_sel_hi:[1,0]
	v_pk_mul_f32 v[166:167], v[6:7], v[6:7]
	v_pk_mul_f32 v[168:169], v[8:9], v[8:9]
	v_pk_mul_f32 v[170:171], v[2:3], v[2:3]
	v_pk_mul_f32 v[172:173], v[4:5], v[4:5]
	v_pk_fma_f32 v[166:167], v[144:145], v[166:167], v[146:147]
	v_pk_fma_f32 v[168:169], v[144:145], v[168:169], v[146:147]
	v_pk_fma_f32 v[170:171], v[144:145], v[170:171], v[146:147]
	v_pk_fma_f32 v[172:173], v[144:145], v[172:173], v[146:147]
	v_pk_mul_f32 v[166:167], v[6:7], v[166:167]
	v_pk_mul_f32 v[168:169], v[8:9], v[168:169]
	v_pk_mul_f32 v[170:171], v[2:3], v[170:171]
	v_pk_mul_f32 v[172:173], v[4:5], v[172:173]
	v_exp_f32_e32 v166, v166
	v_exp_f32_e32 v167, v167
	v_exp_f32_e32 v168, v168
	v_exp_f32_e32 v169, v169
	v_exp_f32_e32 v170, v170
	v_exp_f32_e32 v171, v171
	v_exp_f32_e32 v172, v172
	v_exp_f32_e32 v173, v173
	v_pk_add_f32 v[166:167], v[166:167], 1.0 op_sel_hi:[1,0]
	v_pk_add_f32 v[168:169], v[168:169], 1.0 op_sel_hi:[1,0]
	v_pk_add_f32 v[170:171], v[170:171], 1.0 op_sel_hi:[1,0]
	v_pk_add_f32 v[172:173], v[172:173], 1.0 op_sel_hi:[1,0]
	v_rcp_f32_e32 v166, v166
	v_rcp_f32_e32 v167, v167
	v_rcp_f32_e32 v168, v168
	v_rcp_f32_e32 v169, v169
	v_rcp_f32_e32 v170, v170
	v_rcp_f32_e32 v171, v171
	v_rcp_f32_e32 v172, v172
	v_rcp_f32_e32 v173, v173
	v_pk_mul_f32 v[6:7], v[6:7], v[166:167]
	v_pk_mul_f32 v[8:9], v[8:9], v[168:169]
	v_pk_mul_f32 v[2:3], v[2:3], v[170:171]
	v_pk_mul_f32 v[4:5], v[4:5], v[172:173]
	v_cvt_pk_bf16_f32 v6, v6, v7
	v_cvt_pk_bf16_f32 v7, v8, v9
	v_cvt_pk_bf16_f32 v8, v2, v3
	v_cvt_pk_bf16_f32 v9, v4, v5
	global_store_dwordx4 v141, v[6:9], s[56:57] offset:256
	s_branch .Lpj_done
.Lpj_k0:
	s_lshl_b32 s13, s6, 8
	v_or_b32_e32 v141, s13, v163
	v_mul_u32_u24_e32 v140, 0xe00, v140
	v_lshl_add_u32 v140, v141, 1, v140
	s_waitcnt lgkmcnt(7)
	v_mov_b32_e32 v138, v224
	v_pk_mul_f32 v[126:127], v[126:127], v[138:139] op_sel_hi:[1,0]
	v_pk_mul_f32 v[128:129], v[128:129], v[138:139] op_sel_hi:[1,0]
	v_pk_mul_f32 v[122:123], v[122:123], v[138:139] op_sel_hi:[1,0]
	v_pk_mul_f32 v[124:125], v[124:125], v[138:139] op_sel_hi:[1,0]
	v_cvt_pk_bf16_f32 v126, v126, v127
	v_cvt_pk_bf16_f32 v127, v128, v129
	v_cvt_pk_bf16_f32 v128, v122, v123
	v_cvt_pk_bf16_f32 v129, v124, v125
	global_store_dwordx4 v140, v[126:129], s[36:37]
	v_pk_mul_f32 v[118:119], v[118:119], v[138:139] op_sel_hi:[1,0]
	v_pk_mul_f32 v[120:121], v[120:121], v[138:139] op_sel_hi:[1,0]
	v_pk_mul_f32 v[114:115], v[114:115], v[138:139] op_sel_hi:[1,0]
	v_pk_mul_f32 v[116:117], v[116:117], v[138:139] op_sel_hi:[1,0]
	v_cvt_pk_bf16_f32 v118, v118, v119
	v_cvt_pk_bf16_f32 v119, v120, v121
	v_cvt_pk_bf16_f32 v120, v114, v115
	v_cvt_pk_bf16_f32 v121, v116, v117
	global_store_dwordx4 v140, v[118:121], s[36:37] offset:256
	s_waitcnt lgkmcnt(6)
	v_mov_b32_e32 v138, v225
	v_add_u32_e32 v141, 0xe000, v140
	v_pk_mul_f32 v[110:111], v[110:111], v[138:139] op_sel_hi:[1,0]
	v_pk_mul_f32 v[112:113], v[112:113], v[138:139] op_sel_hi:[1,0]
	v_pk_mul_f32 v[106:107], v[106:107], v[138:139] op_sel_hi:[1,0]
	v_pk_mul_f32 v[108:109], v[108:109], v[138:139] op_sel_hi:[1,0]
	v_cvt_pk_bf16_f32 v110, v110, v111
	v_cvt_pk_bf16_f32 v111, v112, v113
	v_cvt_pk_bf16_f32 v112, v106, v107
	v_cvt_pk_bf16_f32 v113, v108, v109
	global_store_dwordx4 v141, v[110:113], s[36:37]
	v_pk_mul_f32 v[102:103], v[102:103], v[138:139] op_sel_hi:[1,0]
	v_pk_mul_f32 v[104:105], v[104:105], v[138:139] op_sel_hi:[1,0]
	v_pk_mul_f32 v[98:99], v[98:99], v[138:139] op_sel_hi:[1,0]
	v_pk_mul_f32 v[100:101], v[100:101], v[138:139] op_sel_hi:[1,0]
	v_cvt_pk_bf16_f32 v102, v102, v103
	v_cvt_pk_bf16_f32 v103, v104, v105
	v_cvt_pk_bf16_f32 v104, v98, v99
	v_cvt_pk_bf16_f32 v105, v100, v101
	global_store_dwordx4 v141, v[102:105], s[36:37] offset:256
	s_waitcnt lgkmcnt(5)
; __device__ __forceinline__ u32x4 pack8(const f32x4 a, const f32x4 b) { u32x4 w; w.x = cvt_pk_bf16(a[0], a[1]); w.y = cvt_pk_bf16(a[2], a[3]); w.z = cvt_pk_bf16(b[0], b[1]); w.w = cvt_pk_bf16(b[2], b[3]); return w; }
;     __device__ __forceinline__ void operator()(const f32x4 (&acc)[2][2][4][2], const Unit& u, int wr, int wc, int fr, int fq) const {
;     ...
;                 const int row = row0 + ai * 128 + m * 16; const float rs = (u.pm == pm0) ? RS[row & 255] : row_rstd(ss, row);
; #pragma unroll
;                 for (int bj = 0; bj < 2; ++bj) {
;                     f32x4 v[2], e[2];
; #pragma unroll
;                     for (int n = 0; n < 2; ++n) { v[n] = acc[ai][bj][m][n] * rs; e[n] = v[n] * ((v[n] * v[n]) * c3 + c1); }
;                     if (kind != 0) {
; #pragma unroll
;                         for (int n = 0; n < 2; ++n)
; #pragma unroll
;                             for (int j = 0; j < 4; ++j) e[n][j] = __builtin_amdgcn_exp2f(e[n][j]);
; #pragma unroll
;                         for (int n = 0; n < 2; ++n) e[n] = e[n] + 1.0f;
; #pragma unroll
;                         for (int n = 0; n < 2; ++n)
; #pragma unroll
;                             for (int j = 0; j < 4; ++j) e[n][j] = __builtin_amdgcn_rcpf(e[n][j]);
;                         if (kind == 1) { v[0] = v[0] * e[0]; v[1] = v[1] * e[1]; } else { v[0] = e[0]; v[1] = e[1]; }
;                     }
;                     __builtin_nontemporal_store(pack8(v[0], v[1]), (u32x4*)(base + (size_t)row * ld + col0 + bj * 128));
	v_mov_b32_e32 v138, v226
	v_add_u32_e32 v141, 0x1c000, v140
	v_pk_mul_f32 v[94:95], v[94:95], v[138:139] op_sel_hi:[1,0]
	v_pk_mul_f32 v[96:97], v[96:97], v[138:139] op_sel_hi:[1,0]
	v_pk_mul_f32 v[90:91], v[90:91], v[138:139] op_sel_hi:[1,0]
	v_pk_mul_f32 v[92:93], v[92:93], v[138:139] op_sel_hi:[1,0]
	v_cvt_pk_bf16_f32 v94, v94, v95
	v_cvt_pk_bf16_f32 v95, v96, v97
	v_cvt_pk_bf16_f32 v96, v90, v91
	v_cvt_pk_bf16_f32 v97, v92, v93
	global_store_dwordx4 v141, v[94:97], s[36:37]
	v_pk_mul_f32 v[86:87], v[86:87], v[138:139] op_sel_hi:[1,0]
	v_pk_mul_f32 v[88:89], v[88:89], v[138:139] op_sel_hi:[1,0]
	v_pk_mul_f32 v[82:83], v[82:83], v[138:139] op_sel_hi:[1,0]
	v_pk_mul_f32 v[84:85], v[84:85], v[138:139] op_sel_hi:[1,0]
	v_cvt_pk_bf16_f32 v86, v86, v87
	v_cvt_pk_bf16_f32 v87, v88, v89
	v_cvt_pk_bf16_f32 v88, v82, v83
	v_cvt_pk_bf16_f32 v89, v84, v85
	global_store_dwordx4 v141, v[86:89], s[36:37] offset:256
	s_waitcnt lgkmcnt(4)
	v_mov_b32_e32 v138, v227
	v_add_u32_e32 v141, 0x2a000, v140
	v_pk_mul_f32 v[78:79], v[78:79], v[138:139] op_sel_hi:[1,0]
	v_pk_mul_f32 v[80:81], v[80:81], v[138:139] op_sel_hi:[1,0]
	v_pk_mul_f32 v[74:75], v[74:75], v[138:139] op_sel_hi:[1,0]
	v_pk_mul_f32 v[76:77], v[76:77], v[138:139] op_sel_hi:[1,0]
	v_cvt_pk_bf16_f32 v78, v78, v79
	v_cvt_pk_bf16_f32 v79, v80, v81
	v_cvt_pk_bf16_f32 v80, v74, v75
	v_cvt_pk_bf16_f32 v81, v76, v77
	global_store_dwordx4 v141, v[78:81], s[36:37]
	v_pk_mul_f32 v[70:71], v[70:71], v[138:139] op_sel_hi:[1,0]
	v_pk_mul_f32 v[72:73], v[72:73], v[138:139] op_sel_hi:[1,0]
	v_pk_mul_f32 v[66:67], v[66:67], v[138:139] op_sel_hi:[1,0]
	v_pk_mul_f32 v[68:69], v[68:69], v[138:139] op_sel_hi:[1,0]
	v_cvt_pk_bf16_f32 v70, v70, v71
	v_cvt_pk_bf16_f32 v71, v72, v73
	v_cvt_pk_bf16_f32 v72, v66, v67
	v_cvt_pk_bf16_f32 v73, v68, v69
	global_store_dwordx4 v141, v[70:73], s[36:37] offset:256
	s_waitcnt lgkmcnt(3)
	v_mov_b32_e32 v138, v228
	v_add_u32_e32 v141, 0x70000, v140
	v_pk_mul_f32 v[62:63], v[62:63], v[138:139] op_sel_hi:[1,0]
	v_pk_mul_f32 v[64:65], v[64:65], v[138:139] op_sel_hi:[1,0]
	v_pk_mul_f32 v[58:59], v[58:59], v[138:139] op_sel_hi:[1,0]
	v_pk_mul_f32 v[60:61], v[60:61], v[138:139] op_sel_hi:[1,0]
	v_cvt_pk_bf16_f32 v62, v62, v63
	v_cvt_pk_bf16_f32 v63, v64, v65
	v_cvt_pk_bf16_f32 v64, v58, v59
	v_cvt_pk_bf16_f32 v65, v60, v61
	global_store_dwordx4 v141, v[62:65], s[36:37]
	v_pk_mul_f32 v[54:55], v[54:55], v[138:139] op_sel_hi:[1,0]
	v_pk_mul_f32 v[56:57], v[56:57], v[138:139] op_sel_hi:[1,0]
	v_pk_mul_f32 v[50:51], v[50:51], v[138:139] op_sel_hi:[1,0]
	v_pk_mul_f32 v[52:53], v[52:53], v[138:139] op_sel_hi:[1,0]
	v_cvt_pk_bf16_f32 v54, v54, v55
	v_cvt_pk_bf16_f32 v55, v56, v57
	v_cvt_pk_bf16_f32 v56, v50, v51
	v_cvt_pk_bf16_f32 v57, v52, v53
	global_store_dwordx4 v141, v[54:57], s[36:37] offset:256
	s_waitcnt lgkmcnt(2)
	v_mov_b32_e32 v138, v229
	v_add_u32_e32 v141, 0x7e000, v140
	v_pk_mul_f32 v[46:47], v[46:47], v[138:139] op_sel_hi:[1,0]
	v_pk_mul_f32 v[48:49], v[48:49], v[138:139] op_sel_hi:[1,0]
	v_pk_mul_f32 v[42:43], v[42:43], v[138:139] op_sel_hi:[1,0]
	v_pk_mul_f32 v[44:45], v[44:45], v[138:139] op_sel_hi:[1,0]
	v_cvt_pk_bf16_f32 v46, v46, v47
	v_cvt_pk_bf16_f32 v47, v48, v49
	v_cvt_pk_bf16_f32 v48, v42, v43
	v_cvt_pk_bf16_f32 v49, v44, v45
	global_store_dwordx4 v141, v[46:49], s[36:37]
	v_pk_mul_f32 v[38:39], v[38:39], v[138:139] op_sel_hi:[1,0]
	v_pk_mul_f32 v[40:41], v[40:41], v[138:139] op_sel_hi:[1,0]
	v_pk_mul_f32 v[34:35], v[34:35], v[138:139] op_sel_hi:[1,0]
	v_pk_mul_f32 v[36:37], v[36:37], v[138:139] op_sel_hi:[1,0]
	v_cvt_pk_bf16_f32 v38, v38, v39
	v_cvt_pk_bf16_f32 v39, v40, v41
	v_cvt_pk_bf16_f32 v40, v34, v35
	v_cvt_pk_bf16_f32 v41, v36, v37
	global_store_dwordx4 v141, v[38:41], s[36:37] offset:256
	s_waitcnt lgkmcnt(1)
	v_mov_b32_e32 v138, v230
	v_add_u32_e32 v141, 0x8c000, v140
	v_pk_mul_f32 v[30:31], v[30:31], v[138:139] op_sel_hi:[1,0]
	v_pk_mul_f32 v[32:33], v[32:33], v[138:139] op_sel_hi:[1,0]
	v_pk_mul_f32 v[26:27], v[26:27], v[138:139] op_sel_hi:[1,0]
	v_pk_mul_f32 v[28:29], v[28:29], v[138:139] op_sel_hi:[1,0]
	v_cvt_pk_bf16_f32 v30, v30, v31
	v_cvt_pk_bf16_f32 v31, v32, v33
	v_cvt_pk_bf16_f32 v32, v26, v27
	v_cvt_pk_bf16_f32 v33, v28, v29
	global_store_dwordx4 v141, v[30:33], s[36:37]
	v_pk_mul_f32 v[22:23], v[22:23], v[138:139] op_sel_hi:[1,0]
	v_pk_mul_f32 v[24:25], v[24:25], v[138:139] op_sel_hi:[1,0]
	v_pk_mul_f32 v[18:19], v[18:19], v[138:139] op_sel_hi:[1,0]
	v_pk_mul_f32 v[20:21], v[20:21], v[138:139] op_sel_hi:[1,0]
	v_cvt_pk_bf16_f32 v22, v22, v23
	v_cvt_pk_bf16_f32 v23, v24, v25
	v_cvt_pk_bf16_f32 v24, v18, v19
	v_cvt_pk_bf16_f32 v25, v20, v21
	global_store_dwordx4 v141, v[22:25], s[36:37] offset:256
	s_waitcnt lgkmcnt(0)
	v_mov_b32_e32 v138, v231
	v_add_u32_e32 v141, 0x9a000, v140
	v_pk_mul_f32 v[14:15], v[14:15], v[138:139] op_sel_hi:[1,0]
	v_pk_mul_f32 v[16:17], v[16:17], v[138:139] op_sel_hi:[1,0]
	v_pk_mul_f32 v[10:11], v[10:11], v[138:139] op_sel_hi:[1,0]
	v_pk_mul_f32 v[12:13], v[12:13], v[138:139] op_sel_hi:[1,0]
	v_cvt_pk_bf16_f32 v14, v14, v15
	v_cvt_pk_bf16_f32 v15, v16, v17
	v_cvt_pk_bf16_f32 v16, v10, v11
	v_cvt_pk_bf16_f32 v17, v12, v13
	global_store_dwordx4 v141, v[14:17], s[36:37]
	v_pk_mul_f32 v[6:7], v[6:7], v[138:139] op_sel_hi:[1,0]
	v_pk_mul_f32 v[8:9], v[8:9], v[138:139] op_sel_hi:[1,0]
	v_pk_mul_f32 v[2:3], v[2:3], v[138:139] op_sel_hi:[1,0]
	v_pk_mul_f32 v[4:5], v[4:5], v[138:139] op_sel_hi:[1,0]
	v_cvt_pk_bf16_f32 v6, v6, v7
	v_cvt_pk_bf16_f32 v7, v8, v9
	v_cvt_pk_bf16_f32 v8, v2, v3
	v_cvt_pk_bf16_f32 v9, v4, v5
	global_store_dwordx4 v141, v[6:9], s[36:37] offset:256
